# removed the 24 back-to-back s_setprio 0/1 no-op pairs inside the GEMM MFMA segments
# baseline (speedup 1.0000x reference)
.LBB0_293:
	s_cmp_eq_u32 s57, 28
	s_cselect_b32 s42, s10, s19
	s_cselect_b32 s43, s11, s54
	s_cselect_b32 s40, s26, s55
	s_cselect_b32 s41, s27, s56
	s_add_u32 s38, s42, 0x80
	s_addc_u32 s39, s43, 0
	s_add_i32 s60, 0, 0x10000
	s_add_i32 s61, 0, 0x14000
	v_add_u32_e32 v70, s60, v207
	v_add_u32_e32 v110, s61, v207
	ds_read_b128 v[42:45], v70
	ds_read_b128 v[46:49], v70 offset:1024
	ds_read_b128 v[66:69], v70 offset:2048
	ds_read_b128 v[70:73], v70 offset:3072
	ds_read_b128 v[86:89], v110
	ds_read_b128 v[90:93], v110 offset:1024
	ds_read_b128 v[106:109], v110 offset:2048
	ds_read_b128 v[110:113], v110 offset:3072
	s_add_u32 s58, s19, 0x7ff80
	s_addc_u32 s59, s54, 0
	ds_read_b128 v[130:133], v237
	ds_read_b128 v[134:137], v237 offset:1024
	ds_read_b128 v[154:157], v237 offset:2048
	ds_read_b128 v[158:161], v237 offset:3072
	ds_read_b128 v[178:181], v237 offset:4096
	ds_read_b128 v[182:185], v237 offset:5120
	ds_read_b128 v[186:189], v237 offset:6144
	ds_read_b128 v[190:193], v237 offset:7168
	s_add_i32 m0, s46, 0xc000
	v_lshl_add_u64 v[194:195], s[58:59], 0, v[208:209]
	s_add_u32 s58, s58, 0x40000
	s_addc_u32 s59, s59, 0
	global_load_lds_dwordx4 v[194:195], off
	s_add_i32 m0, s46, 0xe000
	v_lshl_add_u64 v[194:195], s[58:59], 0, v[208:209]
	global_load_lds_dwordx4 v[194:195], off
	s_waitcnt vmcnt(8)
	s_waitcnt lgkmcnt(0)
	s_barrier
	s_setprio 1
	s_waitcnt lgkmcnt(0)
	v_mfma_f32_16x16x32_bf16 v[174:177], v[42:45], v[130:133], v[174:177]
	v_mfma_f32_16x16x32_bf16 v[170:173], v[66:69], v[130:133], v[170:173]
	v_mfma_f32_16x16x32_bf16 v[150:153], v[42:45], v[154:157], v[150:153]
	v_mfma_f32_16x16x32_bf16 v[146:149], v[66:69], v[154:157], v[146:149]
	v_mfma_f32_16x16x32_bf16 v[126:129], v[42:45], v[178:181], v[126:129]
	v_mfma_f32_16x16x32_bf16 v[122:125], v[66:69], v[178:181], v[122:125]
	v_mfma_f32_16x16x32_bf16 v[102:105], v[42:45], v[186:189], v[102:105]
	v_mfma_f32_16x16x32_bf16 v[98:101], v[66:69], v[186:189], v[98:101]
	v_mfma_f32_16x16x32_bf16 v[174:177], v[46:49], v[134:137], v[174:177]
	v_mfma_f32_16x16x32_bf16 v[170:173], v[70:73], v[134:137], v[170:173]
	v_mfma_f32_16x16x32_bf16 v[150:153], v[46:49], v[158:161], v[150:153]
	v_mfma_f32_16x16x32_bf16 v[146:149], v[70:73], v[158:161], v[146:149]
	v_mfma_f32_16x16x32_bf16 v[126:129], v[46:49], v[182:185], v[126:129]
	v_mfma_f32_16x16x32_bf16 v[122:125], v[70:73], v[182:185], v[122:125]
	v_mfma_f32_16x16x32_bf16 v[102:105], v[46:49], v[190:193], v[102:105]
	v_mfma_f32_16x16x32_bf16 v[98:101], v[70:73], v[190:193], v[98:101]
	v_mfma_f32_16x16x32_bf16 v[166:169], v[86:89], v[130:133], v[166:169]
	v_mfma_f32_16x16x32_bf16 v[130:133], v[106:109], v[130:133], v[162:165]
	v_mfma_f32_16x16x32_bf16 v[138:141], v[106:109], v[154:157], v[138:141]
	v_mfma_f32_16x16x32_bf16 v[118:121], v[86:89], v[178:181], v[118:121]
	v_mfma_f32_16x16x32_bf16 v[114:117], v[106:109], v[178:181], v[114:117]
	v_mfma_f32_16x16x32_bf16 v[94:97], v[86:89], v[186:189], v[94:97]
	v_mfma_f32_16x16x32_bf16 v[82:85], v[106:109], v[186:189], v[82:85]
	v_mfma_f32_16x16x32_bf16 v[166:169], v[90:93], v[134:137], v[166:169]
	v_mfma_f32_16x16x32_bf16 v[130:133], v[110:113], v[134:137], v[130:133]
	v_mfma_f32_16x16x32_bf16 v[134:137], v[86:89], v[154:157], v[142:145]
	v_mfma_f32_16x16x32_bf16 v[138:141], v[110:113], v[158:161], v[138:141]
	v_mfma_f32_16x16x32_bf16 v[118:121], v[90:93], v[182:185], v[118:121]
	v_mfma_f32_16x16x32_bf16 v[114:117], v[110:113], v[182:185], v[114:117]
	v_mfma_f32_16x16x32_bf16 v[94:97], v[90:93], v[190:193], v[94:97]
	v_mfma_f32_16x16x32_bf16 v[82:85], v[110:113], v[190:193], v[82:85]
	v_mfma_f32_16x16x32_bf16 v[134:137], v[90:93], v[158:161], v[134:137]
	s_setprio 0
	s_barrier
	s_mov_b64 s[58:59], s[40:41]
	ds_read_b128 v[142:145], v237 offset:16384
	ds_read_b128 v[154:157], v237 offset:17408
	ds_read_b128 v[158:161], v237 offset:18432
	ds_read_b128 v[162:165], v237 offset:19456
	ds_read_b128 v[178:181], v237 offset:20480
	ds_read_b128 v[182:185], v237 offset:21504
	ds_read_b128 v[186:189], v237 offset:22528
	ds_read_b128 v[190:193], v237 offset:23552
	s_add_i32 s60, s60, s45
	v_lshl_add_u64 v[194:195], s[58:59], 0, v[202:203]
	s_add_u32 s58, s58, 0x40000
	s_mov_b32 m0, s60
	s_addc_u32 s59, s59, 0
	global_load_lds_dwordx4 v[194:195], off
	s_add_i32 m0, s60, 0x2000
	v_lshl_add_u64 v[194:195], s[58:59], 0, v[202:203]
	s_add_u32 s58, s40, 0x80000
	s_addc_u32 s59, s41, 0
	global_load_lds_dwordx4 v[194:195], off
	s_add_i32 s60, s61, s45
	v_lshl_add_u64 v[194:195], s[58:59], 0, v[202:203]
	s_add_u32 s58, s58, 0x40000
	s_mov_b32 m0, s60
	s_addc_u32 s59, s59, 0
	global_load_lds_dwordx4 v[194:195], off
	s_add_i32 m0, s60, 0x2000
	v_lshl_add_u64 v[194:195], s[58:59], 0, v[202:203]
	s_mov_b64 s[58:59], s[42:43]
	global_load_lds_dwordx4 v[194:195], off
	s_mov_b32 m0, s46
	v_lshl_add_u64 v[194:195], s[58:59], 0, v[208:209]
	s_add_u32 s58, s58, 0x40000
	s_addc_u32 s59, s59, 0
	global_load_lds_dwordx4 v[194:195], off
	s_mov_b32 m0, s47
	v_lshl_add_u64 v[194:195], s[58:59], 0, v[208:209]
	global_load_lds_dwordx4 v[194:195], off
	s_waitcnt vmcnt(8)
	s_waitcnt lgkmcnt(0)
	s_barrier
	s_setprio 1
	s_waitcnt lgkmcnt(0)
	v_mfma_f32_16x16x32_bf16 v[78:81], v[42:45], v[142:145], v[78:81]
	v_mfma_f32_16x16x32_bf16 v[74:77], v[66:69], v[142:145], v[74:77]
	v_mfma_f32_16x16x32_bf16 v[54:57], v[42:45], v[158:161], v[54:57]
	v_mfma_f32_16x16x32_bf16 v[50:53], v[66:69], v[158:161], v[50:53]
	v_mfma_f32_16x16x32_bf16 v[30:33], v[42:45], v[178:181], v[30:33]
	v_mfma_f32_16x16x32_bf16 v[26:29], v[66:69], v[178:181], v[26:29]
	v_mfma_f32_16x16x32_bf16 v[14:17], v[42:45], v[186:189], v[14:17]
	v_mfma_f32_16x16x32_bf16 v[10:13], v[66:69], v[186:189], v[10:13]
	v_mfma_f32_16x16x32_bf16 v[78:81], v[46:49], v[154:157], v[78:81]
	v_mfma_f32_16x16x32_bf16 v[74:77], v[70:73], v[154:157], v[74:77]
	v_mfma_f32_16x16x32_bf16 v[54:57], v[46:49], v[162:165], v[54:57]
	v_mfma_f32_16x16x32_bf16 v[50:53], v[70:73], v[162:165], v[50:53]
	v_mfma_f32_16x16x32_bf16 v[30:33], v[46:49], v[182:185], v[30:33]
	v_mfma_f32_16x16x32_bf16 v[26:29], v[70:73], v[182:185], v[26:29]
	v_mfma_f32_16x16x32_bf16 v[14:17], v[46:49], v[190:193], v[14:17]
	v_mfma_f32_16x16x32_bf16 v[10:13], v[70:73], v[190:193], v[10:13]
	v_mfma_f32_16x16x32_bf16 v[38:41], v[86:89], v[158:161], v[38:41]
	v_mfma_f32_16x16x32_bf16 v[34:37], v[106:109], v[158:161], v[34:37]
	v_mfma_f32_16x16x32_bf16 v[22:25], v[86:89], v[178:181], v[22:25]
	v_mfma_f32_16x16x32_bf16 v[18:21], v[106:109], v[178:181], v[18:21]
	v_mfma_f32_16x16x32_bf16 v[6:9], v[86:89], v[186:189], v[6:9]
	v_mfma_f32_16x16x32_bf16 v[2:5], v[106:109], v[186:189], v[2:5]
	v_mfma_f32_16x16x32_bf16 v[42:45], v[86:89], v[142:145], v[62:65]
	v_mfma_f32_16x16x32_bf16 v[46:49], v[106:109], v[142:145], v[58:61]
	v_mfma_f32_16x16x32_bf16 v[38:41], v[90:93], v[162:165], v[38:41]
	v_mfma_f32_16x16x32_bf16 v[34:37], v[110:113], v[162:165], v[34:37]
	v_mfma_f32_16x16x32_bf16 v[22:25], v[90:93], v[182:185], v[22:25]
	v_mfma_f32_16x16x32_bf16 v[18:21], v[110:113], v[182:185], v[18:21]
	v_mfma_f32_16x16x32_bf16 v[6:9], v[90:93], v[190:193], v[6:9]
	v_mfma_f32_16x16x32_bf16 v[2:5], v[110:113], v[190:193], v[2:5]
	v_mfma_f32_16x16x32_bf16 v[42:45], v[90:93], v[154:157], v[42:45]
	v_mfma_f32_16x16x32_bf16 v[46:49], v[110:113], v[154:157], v[46:49]
	s_setprio 0
	s_barrier
	s_add_i32 s58, 0, 0x18000
	s_add_i32 s59, 0, 0x1c000
	v_add_u32_e32 v70, s58, v207
	v_add_u32_e32 v110, s59, v207
	ds_read_b128 v[58:61], v70
	ds_read_b128 v[62:65], v70 offset:1024
	ds_read_b128 v[66:69], v70 offset:2048
	ds_read_b128 v[70:73], v70 offset:3072
	ds_read_b128 v[86:89], v110
	ds_read_b128 v[90:93], v110 offset:1024
	ds_read_b128 v[106:109], v110 offset:2048
	ds_read_b128 v[110:113], v110 offset:3072
	s_add_u32 s42, s42, 0x80000
	s_addc_u32 s43, s43, 0
	ds_read_b128 v[142:145], v237 offset:32768
	ds_read_b128 v[154:157], v237 offset:33792
	ds_read_b128 v[158:161], v237 offset:34816
	ds_read_b128 v[178:181], v237 offset:35840
	ds_read_b128 v[182:185], v237 offset:36864
	ds_read_b128 v[186:189], v237 offset:37888
	ds_read_b128 v[190:193], v237 offset:38912
	ds_read_b128 v[194:197], v237 offset:39936
	s_mov_b32 m0, s48
	v_lshl_add_u64 v[162:163], s[42:43], 0, v[208:209]
	s_add_u32 s42, s42, 0x40000
	s_addc_u32 s43, s43, 0
	global_load_lds_dwordx4 v[162:163], off
	s_mov_b32 m0, s49
	v_lshl_add_u64 v[162:163], s[42:43], 0, v[208:209]
	global_load_lds_dwordx4 v[162:163], off
	s_waitcnt vmcnt(8)
	s_waitcnt lgkmcnt(0)
	s_barrier
	s_setprio 1
	s_waitcnt lgkmcnt(0)
	v_mfma_f32_16x16x32_bf16 v[162:165], v[58:61], v[142:145], v[174:177]
	v_mfma_f32_16x16x32_bf16 v[174:177], v[62:65], v[154:157], v[162:165]
	v_mfma_f32_16x16x32_bf16 v[162:165], v[66:69], v[142:145], v[170:173]
	v_mfma_f32_16x16x32_bf16 v[150:153], v[58:61], v[158:161], v[150:153]
	v_mfma_f32_16x16x32_bf16 v[146:149], v[66:69], v[158:161], v[146:149]
	v_mfma_f32_16x16x32_bf16 v[126:129], v[58:61], v[182:185], v[126:129]
	v_mfma_f32_16x16x32_bf16 v[122:125], v[66:69], v[182:185], v[122:125]
	v_mfma_f32_16x16x32_bf16 v[102:105], v[58:61], v[190:193], v[102:105]
	v_mfma_f32_16x16x32_bf16 v[98:101], v[66:69], v[190:193], v[98:101]
	v_mfma_f32_16x16x32_bf16 v[170:173], v[70:73], v[154:157], v[162:165]
	v_mfma_f32_16x16x32_bf16 v[150:153], v[62:65], v[178:181], v[150:153]
	v_mfma_f32_16x16x32_bf16 v[146:149], v[70:73], v[178:181], v[146:149]
	v_mfma_f32_16x16x32_bf16 v[126:129], v[62:65], v[186:189], v[126:129]
	v_mfma_f32_16x16x32_bf16 v[122:125], v[70:73], v[186:189], v[122:125]
	v_mfma_f32_16x16x32_bf16 v[102:105], v[62:65], v[194:197], v[102:105]
	v_mfma_f32_16x16x32_bf16 v[98:101], v[70:73], v[194:197], v[98:101]
	v_mfma_f32_16x16x32_bf16 v[162:165], v[86:89], v[142:145], v[166:169]
	v_mfma_f32_16x16x32_bf16 v[130:133], v[106:109], v[142:145], v[130:133]
	v_mfma_f32_16x16x32_bf16 v[166:169], v[90:93], v[154:157], v[162:165]
	v_mfma_f32_16x16x32_bf16 v[162:165], v[110:113], v[154:157], v[130:133]
	v_mfma_f32_16x16x32_bf16 v[130:133], v[86:89], v[158:161], v[134:137]
	v_mfma_f32_16x16x32_bf16 v[142:145], v[90:93], v[178:181], v[130:133]
	v_mfma_f32_16x16x32_bf16 v[130:133], v[106:109], v[158:161], v[138:141]
	v_mfma_f32_16x16x32_bf16 v[118:121], v[86:89], v[182:185], v[118:121]
	v_mfma_f32_16x16x32_bf16 v[114:117], v[106:109], v[182:185], v[114:117]
	v_mfma_f32_16x16x32_bf16 v[94:97], v[86:89], v[190:193], v[94:97]
	v_mfma_f32_16x16x32_bf16 v[82:85], v[106:109], v[190:193], v[82:85]
	v_mfma_f32_16x16x32_bf16 v[138:141], v[110:113], v[178:181], v[130:133]
	v_mfma_f32_16x16x32_bf16 v[118:121], v[90:93], v[186:189], v[118:121]
	v_mfma_f32_16x16x32_bf16 v[114:117], v[110:113], v[186:189], v[114:117]
	v_mfma_f32_16x16x32_bf16 v[94:97], v[90:93], v[194:197], v[94:97]
	v_mfma_f32_16x16x32_bf16 v[82:85], v[110:113], v[194:197], v[82:85]
	s_setprio 0
	s_barrier
	s_add_u32 s42, s40, 0x80
	s_addc_u32 s43, s41, 0
	ds_read_b128 v[130:133], v237 offset:49152
	ds_read_b128 v[134:137], v237 offset:50176
	ds_read_b128 v[154:157], v237 offset:51200
	ds_read_b128 v[158:161], v237 offset:52224
	ds_read_b128 v[178:181], v237 offset:53248
	ds_read_b128 v[182:185], v237 offset:54272
	ds_read_b128 v[186:189], v237 offset:55296
	ds_read_b128 v[190:193], v237 offset:56320
	s_add_i32 s58, s58, s45
	v_lshl_add_u64 v[194:195], s[42:43], 0, v[202:203]
	s_mov_b32 m0, s58
	s_add_u32 s42, s42, 0x40000
	global_load_lds_dwordx4 v[194:195], off
	s_addc_u32 s43, s43, 0
	s_add_i32 m0, s58, 0x2000
	s_add_u32 s40, s40, 0x80080
	s_addc_u32 s41, s41, 0
	v_lshl_add_u64 v[194:195], s[42:43], 0, v[202:203]
	global_load_lds_dwordx4 v[194:195], off
	s_add_i32 s42, s59, s45
	v_lshl_add_u64 v[194:195], s[40:41], 0, v[202:203]
	s_add_u32 s40, s40, 0x40000
	s_mov_b32 m0, s42
	s_addc_u32 s41, s41, 0
	global_load_lds_dwordx4 v[194:195], off
	s_add_i32 m0, s42, 0x2000
	v_lshl_add_u64 v[194:195], s[40:41], 0, v[202:203]
	global_load_lds_dwordx4 v[194:195], off
	s_mov_b32 m0, s50
	v_lshl_add_u64 v[194:195], s[38:39], 0, v[208:209]
	s_add_u32 s38, s38, 0x40000
	s_addc_u32 s39, s39, 0
	global_load_lds_dwordx4 v[194:195], off
	s_mov_b32 m0, s51
	v_lshl_add_u64 v[194:195], s[38:39], 0, v[208:209]
	global_load_lds_dwordx4 v[194:195], off
	s_waitcnt vmcnt(8)
	s_waitcnt lgkmcnt(0)
	s_barrier
	s_setprio 1
	s_waitcnt lgkmcnt(0)
	v_mfma_f32_16x16x32_bf16 v[78:81], v[58:61], v[130:133], v[78:81]
	v_mfma_f32_16x16x32_bf16 v[74:77], v[66:69], v[130:133], v[74:77]
	v_mfma_f32_16x16x32_bf16 v[54:57], v[58:61], v[154:157], v[54:57]
	v_mfma_f32_16x16x32_bf16 v[50:53], v[66:69], v[154:157], v[50:53]
	v_mfma_f32_16x16x32_bf16 v[30:33], v[58:61], v[178:181], v[30:33]
	v_mfma_f32_16x16x32_bf16 v[26:29], v[66:69], v[178:181], v[26:29]
	v_mfma_f32_16x16x32_bf16 v[14:17], v[58:61], v[186:189], v[14:17]
	v_mfma_f32_16x16x32_bf16 v[10:13], v[66:69], v[186:189], v[10:13]
	v_mfma_f32_16x16x32_bf16 v[78:81], v[62:65], v[134:137], v[78:81]
	v_mfma_f32_16x16x32_bf16 v[74:77], v[70:73], v[134:137], v[74:77]
	v_mfma_f32_16x16x32_bf16 v[54:57], v[62:65], v[158:161], v[54:57]
	v_mfma_f32_16x16x32_bf16 v[50:53], v[70:73], v[158:161], v[50:53]
	v_mfma_f32_16x16x32_bf16 v[30:33], v[62:65], v[182:185], v[30:33]
	v_mfma_f32_16x16x32_bf16 v[26:29], v[70:73], v[182:185], v[26:29]
	v_mfma_f32_16x16x32_bf16 v[14:17], v[62:65], v[190:193], v[14:17]
	v_mfma_f32_16x16x32_bf16 v[10:13], v[70:73], v[190:193], v[10:13]
	v_mfma_f32_16x16x32_bf16 v[42:45], v[86:89], v[130:133], v[42:45]
	v_mfma_f32_16x16x32_bf16 v[62:65], v[90:93], v[134:137], v[42:45]
	v_mfma_f32_16x16x32_bf16 v[42:45], v[106:109], v[130:133], v[46:49]
	v_mfma_f32_16x16x32_bf16 v[38:41], v[86:89], v[154:157], v[38:41]
	v_mfma_f32_16x16x32_bf16 v[34:37], v[106:109], v[154:157], v[34:37]
	v_mfma_f32_16x16x32_bf16 v[22:25], v[86:89], v[178:181], v[22:25]
	v_mfma_f32_16x16x32_bf16 v[18:21], v[106:109], v[178:181], v[18:21]
	v_mfma_f32_16x16x32_bf16 v[6:9], v[86:89], v[186:189], v[6:9]
	v_mfma_f32_16x16x32_bf16 v[2:5], v[106:109], v[186:189], v[2:5]
	v_mfma_f32_16x16x32_bf16 v[58:61], v[110:113], v[134:137], v[42:45]
	v_mfma_f32_16x16x32_bf16 v[38:41], v[90:93], v[158:161], v[38:41]
	v_mfma_f32_16x16x32_bf16 v[34:37], v[110:113], v[158:161], v[34:37]
	v_mfma_f32_16x16x32_bf16 v[22:25], v[90:93], v[182:185], v[22:25]
	v_mfma_f32_16x16x32_bf16 v[18:21], v[110:113], v[182:185], v[18:21]
	v_mfma_f32_16x16x32_bf16 v[6:9], v[90:93], v[190:193], v[6:9]
	v_mfma_f32_16x16x32_bf16 v[2:5], v[110:113], v[190:193], v[2:5]
	s_setprio 0
	s_barrier
	s_add_i32 s57, s57, 2
	s_add_u32 s19, s19, 0x100
	s_addc_u32 s54, s54, 0
	s_add_u32 s55, s55, 0x100
	s_addc_u32 s56, s56, 0
	s_cmp_gt_u32 s57, 29
	s_cbranch_scc0 .LBB0_293
	s_and_b64 vcc, exec, s[16:17]
	s_cbranch_vccz .LBB0_296
	s_barrier

.LBB0_1013:
	s_add_i32 s78, s10, 2
	s_cmp_eq_u32 s71, s10
	s_cselect_b32 s46, s4, s28
	s_cselect_b32 s47, s5, s29
	s_cselect_b32 s44, s42, s76
	s_cselect_b32 s45, s43, s77
	s_add_u32 s10, s46, 0x80
	s_addc_u32 s11, s47, 0
	s_add_i32 s79, 0, 0x10000
	s_add_i32 s82, 0, 0x14000
	v_add_u32_e32 v142, s79, v179
	v_add_u32_e32 v160, s82, v179
	ds_read_b128 v[130:133], v142
	ds_read_b128 v[134:137], v142 offset:1024
	ds_read_b128 v[138:141], v142 offset:2048
	ds_read_b128 v[142:145], v142 offset:3072
	ds_read_b128 v[146:149], v160
	ds_read_b128 v[150:153], v160 offset:1024
	ds_read_b128 v[154:157], v160 offset:2048
	ds_read_b128 v[160:163], v160 offset:3072
	s_add_u32 s80, s28, 0x7ff80
	v_add_u32_e32 v240, 0, v178
	s_addc_u32 s81, s29, 0
	ds_read_b128 v[164:167], v240
	ds_read_b128 v[168:171], v240 offset:1024
	ds_read_b128 v[172:175], v240 offset:2048
	ds_read_b128 v[212:215], v240 offset:3072
	ds_read_b128 v[216:219], v240 offset:4096
	ds_read_b128 v[220:223], v240 offset:5120
	ds_read_b128 v[224:227], v240 offset:6144
	ds_read_b128 v[236:239], v240 offset:7168
	s_add_i32 m0, s49, 0xc000
	v_lshl_add_u64 v[176:177], s[80:81], 0, v[158:159]
	s_add_u32 s80, s80, 0x40000
	s_addc_u32 s81, s81, 0
	global_load_lds_dwordx4 v[176:177], off
	s_add_i32 m0, s49, 0xe000
	v_lshl_add_u64 v[176:177], s[80:81], 0, v[158:159]
	global_load_lds_dwordx4 v[176:177], off
	s_waitcnt vmcnt(8)
	s_waitcnt lgkmcnt(0)
	s_barrier
	s_setprio 1
	s_waitcnt lgkmcnt(0)
	v_mfma_f32_16x16x32_bf16 v[126:129], v[130:133], v[164:167], v[126:129]
	v_mfma_f32_16x16x32_bf16 v[122:125], v[138:141], v[164:167], v[122:125]
	v_mfma_f32_16x16x32_bf16 v[114:117], v[130:133], v[172:175], v[114:117]
	v_mfma_f32_16x16x32_bf16 v[106:109], v[138:141], v[172:175], v[106:109]
	v_mfma_f32_16x16x32_bf16 v[98:101], v[130:133], v[216:219], v[98:101]
	v_mfma_f32_16x16x32_bf16 v[90:93], v[138:141], v[216:219], v[90:93]
	v_mfma_f32_16x16x32_bf16 v[82:85], v[130:133], v[224:227], v[82:85]
	v_mfma_f32_16x16x32_bf16 v[74:77], v[138:141], v[224:227], v[74:77]
	v_mfma_f32_16x16x32_bf16 v[126:129], v[134:137], v[168:171], v[126:129]
	v_mfma_f32_16x16x32_bf16 v[122:125], v[142:145], v[168:171], v[122:125]
	v_mfma_f32_16x16x32_bf16 v[114:117], v[134:137], v[212:215], v[114:117]
	v_mfma_f32_16x16x32_bf16 v[106:109], v[142:145], v[212:215], v[106:109]
	v_mfma_f32_16x16x32_bf16 v[98:101], v[134:137], v[220:223], v[98:101]
	v_mfma_f32_16x16x32_bf16 v[90:93], v[142:145], v[220:223], v[90:93]
	v_mfma_f32_16x16x32_bf16 v[82:85], v[134:137], v[236:239], v[82:85]
	v_mfma_f32_16x16x32_bf16 v[74:77], v[142:145], v[236:239], v[74:77]
	v_mfma_f32_16x16x32_bf16 v[118:121], v[146:149], v[164:167], v[118:121]
	v_mfma_f32_16x16x32_bf16 v[110:113], v[154:157], v[164:167], v[110:113]
	v_mfma_f32_16x16x32_bf16 v[102:105], v[146:149], v[172:175], v[102:105]
	v_mfma_f32_16x16x32_bf16 v[94:97], v[154:157], v[172:175], v[94:97]
	v_mfma_f32_16x16x32_bf16 v[86:89], v[146:149], v[216:219], v[86:89]
	v_mfma_f32_16x16x32_bf16 v[78:81], v[154:157], v[216:219], v[78:81]
	v_mfma_f32_16x16x32_bf16 v[70:73], v[146:149], v[224:227], v[70:73]
	v_mfma_f32_16x16x32_bf16 v[66:69], v[154:157], v[224:227], v[66:69]
	v_mfma_f32_16x16x32_bf16 v[118:121], v[150:153], v[168:171], v[118:121]
	v_mfma_f32_16x16x32_bf16 v[110:113], v[160:163], v[168:171], v[110:113]
	v_mfma_f32_16x16x32_bf16 v[102:105], v[150:153], v[212:215], v[102:105]
	v_mfma_f32_16x16x32_bf16 v[94:97], v[160:163], v[212:215], v[94:97]
	v_mfma_f32_16x16x32_bf16 v[86:89], v[150:153], v[220:223], v[86:89]
	v_mfma_f32_16x16x32_bf16 v[78:81], v[160:163], v[220:223], v[78:81]
	v_mfma_f32_16x16x32_bf16 v[70:73], v[150:153], v[236:239], v[70:73]
	v_mfma_f32_16x16x32_bf16 v[66:69], v[160:163], v[236:239], v[66:69]
	s_setprio 0
	s_barrier
	s_mov_b64 s[80:81], s[44:45]
	ds_read_b128 v[164:167], v240 offset:16384
	ds_read_b128 v[168:171], v240 offset:17408
	ds_read_b128 v[172:175], v240 offset:18432
	ds_read_b128 v[212:215], v240 offset:19456
	ds_read_b128 v[216:219], v240 offset:20480
	ds_read_b128 v[220:223], v240 offset:21504
	ds_read_b128 v[224:227], v240 offset:22528
	ds_read_b128 v[236:239], v240 offset:23552
	s_add_i32 s79, s79, s48
	v_lshl_add_u64 v[176:177], s[80:81], 0, v[202:203]
	s_add_u32 s80, s80, 0x30000
	s_mov_b32 m0, s79
	s_addc_u32 s81, s81, 0
	global_load_lds_dwordx4 v[176:177], off
	s_add_i32 m0, s79, 0x2000
	v_lshl_add_u64 v[176:177], s[80:81], 0, v[202:203]
	s_add_u32 s80, s44, 0x60000
	s_addc_u32 s81, s45, 0
	global_load_lds_dwordx4 v[176:177], off
	s_add_i32 s79, s82, s48
	v_lshl_add_u64 v[176:177], s[80:81], 0, v[202:203]
	s_add_u32 s80, s80, 0x30000
	s_mov_b32 m0, s79
	s_addc_u32 s81, s81, 0
	global_load_lds_dwordx4 v[176:177], off
	s_add_i32 m0, s79, 0x2000
	v_lshl_add_u64 v[176:177], s[80:81], 0, v[202:203]
	s_mov_b64 s[80:81], s[46:47]
	global_load_lds_dwordx4 v[176:177], off
	s_mov_b32 m0, s49
	v_lshl_add_u64 v[176:177], s[80:81], 0, v[158:159]
	s_add_u32 s80, s80, 0x40000
	s_addc_u32 s81, s81, 0
	global_load_lds_dwordx4 v[176:177], off
	s_mov_b32 m0, s50
	v_lshl_add_u64 v[176:177], s[80:81], 0, v[158:159]
	global_load_lds_dwordx4 v[176:177], off
	s_waitcnt vmcnt(8)
	s_waitcnt lgkmcnt(0)
	s_barrier
	s_setprio 1
	s_waitcnt lgkmcnt(0)
	v_mfma_f32_16x16x32_bf16 v[62:65], v[130:133], v[164:167], v[62:65]
	v_mfma_f32_16x16x32_bf16 v[58:61], v[138:141], v[164:167], v[58:61]
	v_mfma_f32_16x16x32_bf16 v[50:53], v[130:133], v[172:175], v[50:53]
	v_mfma_f32_16x16x32_bf16 v[42:45], v[138:141], v[172:175], v[42:45]
	v_mfma_f32_16x16x32_bf16 v[34:37], v[130:133], v[216:219], v[34:37]
	v_mfma_f32_16x16x32_bf16 v[26:29], v[138:141], v[216:219], v[26:29]
	v_mfma_f32_16x16x32_bf16 v[18:21], v[130:133], v[224:227], v[18:21]
	v_mfma_f32_16x16x32_bf16 v[10:13], v[138:141], v[224:227], v[10:13]
	v_mfma_f32_16x16x32_bf16 v[62:65], v[134:137], v[168:171], v[62:65]
	v_mfma_f32_16x16x32_bf16 v[58:61], v[142:145], v[168:171], v[58:61]
	v_mfma_f32_16x16x32_bf16 v[50:53], v[134:137], v[212:215], v[50:53]
	v_mfma_f32_16x16x32_bf16 v[42:45], v[142:145], v[212:215], v[42:45]
	v_mfma_f32_16x16x32_bf16 v[34:37], v[134:137], v[220:223], v[34:37]
	v_mfma_f32_16x16x32_bf16 v[26:29], v[142:145], v[220:223], v[26:29]
	v_mfma_f32_16x16x32_bf16 v[18:21], v[134:137], v[236:239], v[18:21]
	v_mfma_f32_16x16x32_bf16 v[10:13], v[142:145], v[236:239], v[10:13]
	v_mfma_f32_16x16x32_bf16 v[54:57], v[146:149], v[164:167], v[54:57]
	v_mfma_f32_16x16x32_bf16 v[46:49], v[154:157], v[164:167], v[46:49]
	v_mfma_f32_16x16x32_bf16 v[38:41], v[146:149], v[172:175], v[38:41]
	v_mfma_f32_16x16x32_bf16 v[30:33], v[154:157], v[172:175], v[30:33]
	v_mfma_f32_16x16x32_bf16 v[22:25], v[146:149], v[216:219], v[22:25]
	v_mfma_f32_16x16x32_bf16 v[14:17], v[154:157], v[216:219], v[14:17]
	v_mfma_f32_16x16x32_bf16 v[6:9], v[146:149], v[224:227], v[6:9]
	v_mfma_f32_16x16x32_bf16 v[2:5], v[154:157], v[224:227], v[2:5]
	v_mfma_f32_16x16x32_bf16 v[54:57], v[150:153], v[168:171], v[54:57]
	v_mfma_f32_16x16x32_bf16 v[46:49], v[160:163], v[168:171], v[46:49]
	v_mfma_f32_16x16x32_bf16 v[38:41], v[150:153], v[212:215], v[38:41]
	v_mfma_f32_16x16x32_bf16 v[30:33], v[160:163], v[212:215], v[30:33]
	v_mfma_f32_16x16x32_bf16 v[22:25], v[150:153], v[220:223], v[22:25]
	v_mfma_f32_16x16x32_bf16 v[14:17], v[160:163], v[220:223], v[14:17]
	v_mfma_f32_16x16x32_bf16 v[6:9], v[150:153], v[236:239], v[6:9]
	v_mfma_f32_16x16x32_bf16 v[2:5], v[160:163], v[236:239], v[2:5]
	s_setprio 0
	s_barrier
	s_add_i32 s79, 0, 0x18000
	s_add_i32 s80, 0, 0x1c000
	v_add_u32_e32 v142, s79, v179
	v_add_u32_e32 v160, s80, v179
	ds_read_b128 v[130:133], v142
	ds_read_b128 v[134:137], v142 offset:1024
	ds_read_b128 v[138:141], v142 offset:2048
	ds_read_b128 v[142:145], v142 offset:3072
	ds_read_b128 v[146:149], v160
	ds_read_b128 v[150:153], v160 offset:1024
	ds_read_b128 v[154:157], v160 offset:2048
	ds_read_b128 v[160:163], v160 offset:3072
	s_add_u32 s46, s46, 0x80000
	s_addc_u32 s47, s47, 0
	ds_read_b128 v[164:167], v240 offset:32768
	ds_read_b128 v[168:171], v240 offset:33792
	ds_read_b128 v[172:175], v240 offset:34816
	ds_read_b128 v[212:215], v240 offset:35840
	ds_read_b128 v[216:219], v240 offset:36864
	ds_read_b128 v[220:223], v240 offset:37888
	ds_read_b128 v[224:227], v240 offset:38912
	ds_read_b128 v[236:239], v240 offset:39936
	s_mov_b32 m0, s51
	v_lshl_add_u64 v[176:177], s[46:47], 0, v[158:159]
	s_add_u32 s46, s46, 0x40000
	s_addc_u32 s47, s47, 0
	global_load_lds_dwordx4 v[176:177], off
	s_mov_b32 m0, s52
	v_lshl_add_u64 v[176:177], s[46:47], 0, v[158:159]
	global_load_lds_dwordx4 v[176:177], off
	s_waitcnt vmcnt(8)
	s_waitcnt lgkmcnt(0)
	s_barrier
	s_setprio 1
	s_waitcnt lgkmcnt(0)
	v_mfma_f32_16x16x32_bf16 v[126:129], v[130:133], v[164:167], v[126:129]
	v_mfma_f32_16x16x32_bf16 v[122:125], v[138:141], v[164:167], v[122:125]
	v_mfma_f32_16x16x32_bf16 v[114:117], v[130:133], v[172:175], v[114:117]
	v_mfma_f32_16x16x32_bf16 v[106:109], v[138:141], v[172:175], v[106:109]
	v_mfma_f32_16x16x32_bf16 v[98:101], v[130:133], v[216:219], v[98:101]
	v_mfma_f32_16x16x32_bf16 v[90:93], v[138:141], v[216:219], v[90:93]
	v_mfma_f32_16x16x32_bf16 v[82:85], v[130:133], v[224:227], v[82:85]
	v_mfma_f32_16x16x32_bf16 v[74:77], v[138:141], v[224:227], v[74:77]
	v_mfma_f32_16x16x32_bf16 v[126:129], v[134:137], v[168:171], v[126:129]
	v_mfma_f32_16x16x32_bf16 v[122:125], v[142:145], v[168:171], v[122:125]
	v_mfma_f32_16x16x32_bf16 v[114:117], v[134:137], v[212:215], v[114:117]
	v_mfma_f32_16x16x32_bf16 v[106:109], v[142:145], v[212:215], v[106:109]
	v_mfma_f32_16x16x32_bf16 v[98:101], v[134:137], v[220:223], v[98:101]
	v_mfma_f32_16x16x32_bf16 v[90:93], v[142:145], v[220:223], v[90:93]
	v_mfma_f32_16x16x32_bf16 v[82:85], v[134:137], v[236:239], v[82:85]
	v_mfma_f32_16x16x32_bf16 v[74:77], v[142:145], v[236:239], v[74:77]
	v_mfma_f32_16x16x32_bf16 v[118:121], v[146:149], v[164:167], v[118:121]
	v_mfma_f32_16x16x32_bf16 v[110:113], v[154:157], v[164:167], v[110:113]
	v_mfma_f32_16x16x32_bf16 v[102:105], v[146:149], v[172:175], v[102:105]
	v_mfma_f32_16x16x32_bf16 v[94:97], v[154:157], v[172:175], v[94:97]
	v_mfma_f32_16x16x32_bf16 v[86:89], v[146:149], v[216:219], v[86:89]
	v_mfma_f32_16x16x32_bf16 v[78:81], v[154:157], v[216:219], v[78:81]
	v_mfma_f32_16x16x32_bf16 v[70:73], v[146:149], v[224:227], v[70:73]
	v_mfma_f32_16x16x32_bf16 v[66:69], v[154:157], v[224:227], v[66:69]
	v_mfma_f32_16x16x32_bf16 v[118:121], v[150:153], v[168:171], v[118:121]
	v_mfma_f32_16x16x32_bf16 v[110:113], v[160:163], v[168:171], v[110:113]
	v_mfma_f32_16x16x32_bf16 v[102:105], v[150:153], v[212:215], v[102:105]
	v_mfma_f32_16x16x32_bf16 v[94:97], v[160:163], v[212:215], v[94:97]
	v_mfma_f32_16x16x32_bf16 v[86:89], v[150:153], v[220:223], v[86:89]
	v_mfma_f32_16x16x32_bf16 v[78:81], v[160:163], v[220:223], v[78:81]
	v_mfma_f32_16x16x32_bf16 v[70:73], v[150:153], v[236:239], v[70:73]
	v_mfma_f32_16x16x32_bf16 v[66:69], v[160:163], v[236:239], v[66:69]
	s_setprio 0
	s_barrier
	s_add_u32 s46, s44, 0x80
	s_addc_u32 s47, s45, 0
	ds_read_b128 v[164:167], v240 offset:49152
	ds_read_b128 v[168:171], v240 offset:50176
	ds_read_b128 v[172:175], v240 offset:51200
	ds_read_b128 v[212:215], v240 offset:52224
	ds_read_b128 v[216:219], v240 offset:53248
	ds_read_b128 v[220:223], v240 offset:54272
	ds_read_b128 v[224:227], v240 offset:55296
	ds_read_b128 v[236:239], v240 offset:56320
	s_add_i32 s79, s79, s48
	v_lshl_add_u64 v[176:177], s[46:47], 0, v[202:203]
	s_mov_b32 m0, s79
	s_add_u32 s46, s46, 0x30000
	global_load_lds_dwordx4 v[176:177], off
	s_addc_u32 s47, s47, 0
	s_add_i32 m0, s79, 0x2000
	s_add_u32 s44, s44, 0x60080
	s_addc_u32 s45, s45, 0
	v_lshl_add_u64 v[176:177], s[46:47], 0, v[202:203]
	global_load_lds_dwordx4 v[176:177], off
	s_add_i32 s46, s80, s48
	v_lshl_add_u64 v[176:177], s[44:45], 0, v[202:203]
	s_add_u32 s44, s44, 0x30000
	s_mov_b32 m0, s46
	s_addc_u32 s45, s45, 0
	global_load_lds_dwordx4 v[176:177], off
	s_add_i32 m0, s46, 0x2000
	v_lshl_add_u64 v[176:177], s[44:45], 0, v[202:203]
	global_load_lds_dwordx4 v[176:177], off
	s_mov_b32 m0, s53
	v_lshl_add_u64 v[176:177], s[10:11], 0, v[158:159]
	s_add_u32 s10, s10, 0x40000
	s_addc_u32 s11, s11, 0
	global_load_lds_dwordx4 v[176:177], off
	s_mov_b32 m0, s54
	v_lshl_add_u64 v[176:177], s[10:11], 0, v[158:159]
	global_load_lds_dwordx4 v[176:177], off
	s_waitcnt vmcnt(8)
	s_waitcnt lgkmcnt(0)
	s_barrier
	s_setprio 1
	s_waitcnt lgkmcnt(0)
	v_mfma_f32_16x16x32_bf16 v[62:65], v[130:133], v[164:167], v[62:65]
	v_mfma_f32_16x16x32_bf16 v[58:61], v[138:141], v[164:167], v[58:61]
	v_mfma_f32_16x16x32_bf16 v[50:53], v[130:133], v[172:175], v[50:53]
	v_mfma_f32_16x16x32_bf16 v[42:45], v[138:141], v[172:175], v[42:45]
	v_mfma_f32_16x16x32_bf16 v[34:37], v[130:133], v[216:219], v[34:37]
	v_mfma_f32_16x16x32_bf16 v[26:29], v[138:141], v[216:219], v[26:29]
	v_mfma_f32_16x16x32_bf16 v[18:21], v[130:133], v[224:227], v[18:21]
	v_mfma_f32_16x16x32_bf16 v[10:13], v[138:141], v[224:227], v[10:13]
	v_mfma_f32_16x16x32_bf16 v[62:65], v[134:137], v[168:171], v[62:65]
	v_mfma_f32_16x16x32_bf16 v[58:61], v[142:145], v[168:171], v[58:61]
	v_mfma_f32_16x16x32_bf16 v[50:53], v[134:137], v[212:215], v[50:53]
	v_mfma_f32_16x16x32_bf16 v[42:45], v[142:145], v[212:215], v[42:45]
	v_mfma_f32_16x16x32_bf16 v[34:37], v[134:137], v[220:223], v[34:37]
	v_mfma_f32_16x16x32_bf16 v[26:29], v[142:145], v[220:223], v[26:29]
	v_mfma_f32_16x16x32_bf16 v[18:21], v[134:137], v[236:239], v[18:21]
	v_mfma_f32_16x16x32_bf16 v[10:13], v[142:145], v[236:239], v[10:13]
	v_mfma_f32_16x16x32_bf16 v[54:57], v[146:149], v[164:167], v[54:57]
	v_mfma_f32_16x16x32_bf16 v[46:49], v[154:157], v[164:167], v[46:49]
	v_mfma_f32_16x16x32_bf16 v[38:41], v[146:149], v[172:175], v[38:41]
	v_mfma_f32_16x16x32_bf16 v[30:33], v[154:157], v[172:175], v[30:33]
	v_mfma_f32_16x16x32_bf16 v[22:25], v[146:149], v[216:219], v[22:25]
	v_mfma_f32_16x16x32_bf16 v[14:17], v[154:157], v[216:219], v[14:17]
	v_mfma_f32_16x16x32_bf16 v[6:9], v[146:149], v[224:227], v[6:9]
	v_mfma_f32_16x16x32_bf16 v[2:5], v[154:157], v[224:227], v[2:5]
	v_mfma_f32_16x16x32_bf16 v[54:57], v[150:153], v[168:171], v[54:57]
	v_mfma_f32_16x16x32_bf16 v[46:49], v[160:163], v[168:171], v[46:49]
	v_mfma_f32_16x16x32_bf16 v[38:41], v[150:153], v[212:215], v[38:41]
	v_mfma_f32_16x16x32_bf16 v[30:33], v[160:163], v[212:215], v[30:33]
	v_mfma_f32_16x16x32_bf16 v[22:25], v[150:153], v[220:223], v[22:25]
	v_mfma_f32_16x16x32_bf16 v[14:17], v[160:163], v[220:223], v[14:17]
	v_mfma_f32_16x16x32_bf16 v[6:9], v[150:153], v[236:239], v[6:9]
	v_mfma_f32_16x16x32_bf16 v[2:5], v[160:163], v[236:239], v[2:5]
	s_setprio 0
	s_barrier
	s_add_u32 s28, s28, 0x100
	s_addc_u32 s29, s29, 0
	s_add_u32 s76, s76, 0x100
	s_addc_u32 s77, s77, 0
	s_cmp_ge_i32 s78, s69
	s_mov_b32 s10, s78
	s_cbranch_scc0 .LBB0_1013
	s_and_b64 vcc, exec, s[18:19]
	s_cbranch_vccz .LBB0_1016
	s_barrier

.LBB0_1026:
	s_add_i32 s28, s10, 2
	s_cmp_eq_u32 s71, s10
	s_cselect_b32 s46, s4, s74
	s_cselect_b32 s47, s5, s75
	s_cselect_b32 s44, s42, s72
	s_cselect_b32 s45, s43, s73
	s_add_u32 s10, s46, 0x80
	s_addc_u32 s11, s47, 0
	s_add_i32 s29, 0, 0x10000
	s_add_i32 s78, 0, 0x14000
	v_add_u32_e32 v142, s29, v179
	v_add_u32_e32 v160, s78, v179
	ds_read_b128 v[130:133], v142
	ds_read_b128 v[134:137], v142 offset:1024
	ds_read_b128 v[138:141], v142 offset:2048
	ds_read_b128 v[142:145], v142 offset:3072
	ds_read_b128 v[146:149], v160
	ds_read_b128 v[150:153], v160 offset:1024
	ds_read_b128 v[154:157], v160 offset:2048
	ds_read_b128 v[160:163], v160 offset:3072
	s_add_u32 s76, s74, 0x7ff80
	v_add_u32_e32 v200, 0, v178
	s_addc_u32 s77, s75, 0
	ds_read_b128 v[164:167], v200
	ds_read_b128 v[168:171], v200 offset:1024
	ds_read_b128 v[172:175], v200 offset:2048
	ds_read_b128 v[180:183], v200 offset:3072
	ds_read_b128 v[184:187], v200 offset:4096
	ds_read_b128 v[188:191], v200 offset:5120
	ds_read_b128 v[192:195], v200 offset:6144
	ds_read_b128 v[196:199], v200 offset:7168
	s_add_i32 m0, s49, 0xc000
	v_lshl_add_u64 v[176:177], s[76:77], 0, v[158:159]
	s_add_u32 s76, s76, 0x40000
	s_addc_u32 s77, s77, 0
	global_load_lds_dwordx4 v[176:177], off
	s_add_i32 m0, s49, 0xe000
	v_lshl_add_u64 v[176:177], s[76:77], 0, v[158:159]
	global_load_lds_dwordx4 v[176:177], off
	s_waitcnt vmcnt(8)
	s_waitcnt lgkmcnt(0)
	s_barrier
	s_setprio 1
	s_waitcnt lgkmcnt(0)
	v_mfma_i32_16x16x64_i8 v[126:129], v[130:133], v[164:167], v[126:129]
	v_mfma_i32_16x16x64_i8 v[122:125], v[138:141], v[164:167], v[122:125]
	v_mfma_i32_16x16x64_i8 v[118:121], v[130:133], v[172:175], v[118:121]
	v_mfma_i32_16x16x64_i8 v[114:117], v[138:141], v[172:175], v[114:117]
	v_mfma_i32_16x16x64_i8 v[102:105], v[130:133], v[184:187], v[102:105]
	v_mfma_i32_16x16x64_i8 v[98:101], v[138:141], v[184:187], v[98:101]
	v_mfma_i32_16x16x64_i8 v[86:89], v[130:133], v[192:195], v[86:89]
	v_mfma_i32_16x16x64_i8 v[82:85], v[138:141], v[192:195], v[82:85]
	v_mfma_i32_16x16x64_i8 v[126:129], v[134:137], v[168:171], v[126:129]
	v_mfma_i32_16x16x64_i8 v[122:125], v[142:145], v[168:171], v[122:125]
	v_mfma_i32_16x16x64_i8 v[118:121], v[134:137], v[180:183], v[118:121]
	v_mfma_i32_16x16x64_i8 v[114:117], v[142:145], v[180:183], v[114:117]
	v_mfma_i32_16x16x64_i8 v[102:105], v[134:137], v[188:191], v[102:105]
	v_mfma_i32_16x16x64_i8 v[98:101], v[142:145], v[188:191], v[98:101]
	v_mfma_i32_16x16x64_i8 v[86:89], v[134:137], v[196:199], v[86:89]
	v_mfma_i32_16x16x64_i8 v[82:85], v[142:145], v[196:199], v[82:85]
	v_mfma_i32_16x16x64_i8 v[110:113], v[146:149], v[164:167], v[110:113]
	v_mfma_i32_16x16x64_i8 v[106:109], v[154:157], v[164:167], v[106:109]
	v_mfma_i32_16x16x64_i8 v[94:97], v[146:149], v[172:175], v[94:97]
	v_mfma_i32_16x16x64_i8 v[90:93], v[154:157], v[172:175], v[90:93]
	v_mfma_i32_16x16x64_i8 v[78:81], v[146:149], v[184:187], v[78:81]
	v_mfma_i32_16x16x64_i8 v[74:77], v[154:157], v[184:187], v[74:77]
	v_mfma_i32_16x16x64_i8 v[70:73], v[146:149], v[192:195], v[70:73]
	v_mfma_i32_16x16x64_i8 v[66:69], v[154:157], v[192:195], v[66:69]
	v_mfma_i32_16x16x64_i8 v[110:113], v[150:153], v[168:171], v[110:113]
	v_mfma_i32_16x16x64_i8 v[106:109], v[160:163], v[168:171], v[106:109]
	v_mfma_i32_16x16x64_i8 v[94:97], v[150:153], v[180:183], v[94:97]
	v_mfma_i32_16x16x64_i8 v[90:93], v[160:163], v[180:183], v[90:93]
	v_mfma_i32_16x16x64_i8 v[78:81], v[150:153], v[188:191], v[78:81]
	v_mfma_i32_16x16x64_i8 v[74:77], v[160:163], v[188:191], v[74:77]
	v_mfma_i32_16x16x64_i8 v[70:73], v[150:153], v[196:199], v[70:73]
	v_mfma_i32_16x16x64_i8 v[66:69], v[160:163], v[196:199], v[66:69]
	s_setprio 0
	s_barrier
	s_mov_b64 s[76:77], s[44:45]
	ds_read_b128 v[164:167], v200 offset:16384
	ds_read_b128 v[168:171], v200 offset:17408
	ds_read_b128 v[172:175], v200 offset:18432
	ds_read_b128 v[180:183], v200 offset:19456
	ds_read_b128 v[184:187], v200 offset:20480
	ds_read_b128 v[188:191], v200 offset:21504
	ds_read_b128 v[192:195], v200 offset:22528
	ds_read_b128 v[196:199], v200 offset:23552
	s_add_i32 s29, s29, s48
	v_lshl_add_u64 v[176:177], s[76:77], 0, v[202:203]
	s_add_u32 s76, s76, 0x30000
	s_mov_b32 m0, s29
	s_addc_u32 s77, s77, 0
	global_load_lds_dwordx4 v[176:177], off
	s_add_i32 m0, s29, 0x2000
	v_lshl_add_u64 v[176:177], s[76:77], 0, v[202:203]
	s_add_u32 s76, s44, 0x60000
	s_addc_u32 s77, s45, 0
	global_load_lds_dwordx4 v[176:177], off
	s_add_i32 s29, s78, s48
	v_lshl_add_u64 v[176:177], s[76:77], 0, v[202:203]
	s_add_u32 s76, s76, 0x30000
	s_mov_b32 m0, s29
	s_addc_u32 s77, s77, 0
	global_load_lds_dwordx4 v[176:177], off
	s_add_i32 m0, s29, 0x2000
	v_lshl_add_u64 v[176:177], s[76:77], 0, v[202:203]
	s_mov_b64 s[76:77], s[46:47]
	global_load_lds_dwordx4 v[176:177], off
	s_mov_b32 m0, s49
	v_lshl_add_u64 v[176:177], s[76:77], 0, v[158:159]
	s_add_u32 s76, s76, 0x40000
	s_addc_u32 s77, s77, 0
	global_load_lds_dwordx4 v[176:177], off
	s_mov_b32 m0, s50
	v_lshl_add_u64 v[176:177], s[76:77], 0, v[158:159]
	global_load_lds_dwordx4 v[176:177], off
	s_waitcnt vmcnt(8)
	s_waitcnt lgkmcnt(0)
	s_barrier
	s_setprio 1
	s_waitcnt lgkmcnt(0)
	v_mfma_i32_16x16x64_i8 v[62:65], v[130:133], v[164:167], v[62:65]
	v_mfma_i32_16x16x64_i8 v[58:61], v[138:141], v[164:167], v[58:61]
	v_mfma_i32_16x16x64_i8 v[54:57], v[130:133], v[172:175], v[54:57]
	v_mfma_i32_16x16x64_i8 v[50:53], v[138:141], v[172:175], v[50:53]
	v_mfma_i32_16x16x64_i8 v[38:41], v[130:133], v[184:187], v[38:41]
	v_mfma_i32_16x16x64_i8 v[34:37], v[138:141], v[184:187], v[34:37]
	v_mfma_i32_16x16x64_i8 v[14:17], v[130:133], v[192:195], v[14:17]
	v_mfma_i32_16x16x64_i8 v[10:13], v[138:141], v[192:195], v[10:13]
	v_mfma_i32_16x16x64_i8 v[62:65], v[134:137], v[168:171], v[62:65]
	v_mfma_i32_16x16x64_i8 v[58:61], v[142:145], v[168:171], v[58:61]
	v_mfma_i32_16x16x64_i8 v[54:57], v[134:137], v[180:183], v[54:57]
	v_mfma_i32_16x16x64_i8 v[50:53], v[142:145], v[180:183], v[50:53]
	v_mfma_i32_16x16x64_i8 v[38:41], v[134:137], v[188:191], v[38:41]
	v_mfma_i32_16x16x64_i8 v[34:37], v[142:145], v[188:191], v[34:37]
	v_mfma_i32_16x16x64_i8 v[14:17], v[134:137], v[196:199], v[14:17]
	v_mfma_i32_16x16x64_i8 v[10:13], v[142:145], v[196:199], v[10:13]
	v_mfma_i32_16x16x64_i8 v[46:49], v[146:149], v[164:167], v[46:49]
	v_mfma_i32_16x16x64_i8 v[42:45], v[154:157], v[164:167], v[42:45]
	v_mfma_i32_16x16x64_i8 v[30:33], v[146:149], v[172:175], v[30:33]
	v_mfma_i32_16x16x64_i8 v[26:29], v[154:157], v[172:175], v[26:29]
	v_mfma_i32_16x16x64_i8 v[22:25], v[146:149], v[184:187], v[22:25]
	v_mfma_i32_16x16x64_i8 v[18:21], v[154:157], v[184:187], v[18:21]
	v_mfma_i32_16x16x64_i8 v[6:9], v[146:149], v[192:195], v[6:9]
	v_mfma_i32_16x16x64_i8 v[2:5], v[154:157], v[192:195], v[2:5]
	v_mfma_i32_16x16x64_i8 v[46:49], v[150:153], v[168:171], v[46:49]
	v_mfma_i32_16x16x64_i8 v[42:45], v[160:163], v[168:171], v[42:45]
	v_mfma_i32_16x16x64_i8 v[30:33], v[150:153], v[180:183], v[30:33]
	v_mfma_i32_16x16x64_i8 v[26:29], v[160:163], v[180:183], v[26:29]
	v_mfma_i32_16x16x64_i8 v[22:25], v[150:153], v[188:191], v[22:25]
	v_mfma_i32_16x16x64_i8 v[18:21], v[160:163], v[188:191], v[18:21]
	v_mfma_i32_16x16x64_i8 v[6:9], v[150:153], v[196:199], v[6:9]
	v_mfma_i32_16x16x64_i8 v[2:5], v[160:163], v[196:199], v[2:5]
	s_setprio 0
	s_barrier
	s_add_i32 s29, 0, 0x18000
	s_add_i32 s76, 0, 0x1c000
	v_add_u32_e32 v142, s29, v179
	v_add_u32_e32 v160, s76, v179
	ds_read_b128 v[130:133], v142
	ds_read_b128 v[134:137], v142 offset:1024
	ds_read_b128 v[138:141], v142 offset:2048
	ds_read_b128 v[142:145], v142 offset:3072
	ds_read_b128 v[146:149], v160
	ds_read_b128 v[150:153], v160 offset:1024
	ds_read_b128 v[154:157], v160 offset:2048
	ds_read_b128 v[160:163], v160 offset:3072
	s_add_u32 s46, s46, 0x80000
	s_addc_u32 s47, s47, 0
	ds_read_b128 v[164:167], v200 offset:32768
	ds_read_b128 v[168:171], v200 offset:33792
	ds_read_b128 v[172:175], v200 offset:34816
	ds_read_b128 v[180:183], v200 offset:35840
	ds_read_b128 v[184:187], v200 offset:36864
	ds_read_b128 v[188:191], v200 offset:37888
	ds_read_b128 v[192:195], v200 offset:38912
	ds_read_b128 v[196:199], v200 offset:39936
	s_mov_b32 m0, s51
	v_lshl_add_u64 v[176:177], s[46:47], 0, v[158:159]
	s_add_u32 s46, s46, 0x40000
	s_addc_u32 s47, s47, 0
	global_load_lds_dwordx4 v[176:177], off
	s_mov_b32 m0, s52
	v_lshl_add_u64 v[176:177], s[46:47], 0, v[158:159]
	global_load_lds_dwordx4 v[176:177], off
	s_waitcnt vmcnt(8)
	s_waitcnt lgkmcnt(0)
	s_barrier
	s_setprio 1
	s_waitcnt lgkmcnt(0)
	v_mfma_i32_16x16x64_i8 v[126:129], v[130:133], v[164:167], v[126:129]
	v_mfma_i32_16x16x64_i8 v[122:125], v[138:141], v[164:167], v[122:125]
	v_mfma_i32_16x16x64_i8 v[118:121], v[130:133], v[172:175], v[118:121]
	v_mfma_i32_16x16x64_i8 v[114:117], v[138:141], v[172:175], v[114:117]
	v_mfma_i32_16x16x64_i8 v[102:105], v[130:133], v[184:187], v[102:105]
	v_mfma_i32_16x16x64_i8 v[98:101], v[138:141], v[184:187], v[98:101]
	v_mfma_i32_16x16x64_i8 v[86:89], v[130:133], v[192:195], v[86:89]
	v_mfma_i32_16x16x64_i8 v[82:85], v[138:141], v[192:195], v[82:85]
	v_mfma_i32_16x16x64_i8 v[126:129], v[134:137], v[168:171], v[126:129]
	v_mfma_i32_16x16x64_i8 v[122:125], v[142:145], v[168:171], v[122:125]
	v_mfma_i32_16x16x64_i8 v[118:121], v[134:137], v[180:183], v[118:121]
	v_mfma_i32_16x16x64_i8 v[114:117], v[142:145], v[180:183], v[114:117]
	v_mfma_i32_16x16x64_i8 v[102:105], v[134:137], v[188:191], v[102:105]
	v_mfma_i32_16x16x64_i8 v[98:101], v[142:145], v[188:191], v[98:101]
	v_mfma_i32_16x16x64_i8 v[86:89], v[134:137], v[196:199], v[86:89]
	v_mfma_i32_16x16x64_i8 v[82:85], v[142:145], v[196:199], v[82:85]
	v_mfma_i32_16x16x64_i8 v[110:113], v[146:149], v[164:167], v[110:113]
	v_mfma_i32_16x16x64_i8 v[106:109], v[154:157], v[164:167], v[106:109]
	v_mfma_i32_16x16x64_i8 v[94:97], v[146:149], v[172:175], v[94:97]
	v_mfma_i32_16x16x64_i8 v[90:93], v[154:157], v[172:175], v[90:93]
	v_mfma_i32_16x16x64_i8 v[78:81], v[146:149], v[184:187], v[78:81]
	v_mfma_i32_16x16x64_i8 v[74:77], v[154:157], v[184:187], v[74:77]
	v_mfma_i32_16x16x64_i8 v[70:73], v[146:149], v[192:195], v[70:73]
	v_mfma_i32_16x16x64_i8 v[66:69], v[154:157], v[192:195], v[66:69]
	v_mfma_i32_16x16x64_i8 v[110:113], v[150:153], v[168:171], v[110:113]
	v_mfma_i32_16x16x64_i8 v[106:109], v[160:163], v[168:171], v[106:109]
	v_mfma_i32_16x16x64_i8 v[94:97], v[150:153], v[180:183], v[94:97]
	v_mfma_i32_16x16x64_i8 v[90:93], v[160:163], v[180:183], v[90:93]
	v_mfma_i32_16x16x64_i8 v[78:81], v[150:153], v[188:191], v[78:81]
	v_mfma_i32_16x16x64_i8 v[74:77], v[160:163], v[188:191], v[74:77]
	v_mfma_i32_16x16x64_i8 v[70:73], v[150:153], v[196:199], v[70:73]
	v_mfma_i32_16x16x64_i8 v[66:69], v[160:163], v[196:199], v[66:69]
	s_setprio 0
	s_barrier
	s_add_u32 s46, s44, 0x80
	s_addc_u32 s47, s45, 0
	ds_read_b128 v[164:167], v200 offset:49152
	ds_read_b128 v[168:171], v200 offset:50176
	ds_read_b128 v[172:175], v200 offset:51200
	ds_read_b128 v[180:183], v200 offset:52224
	ds_read_b128 v[184:187], v200 offset:53248
	ds_read_b128 v[188:191], v200 offset:54272
	ds_read_b128 v[192:195], v200 offset:55296
	ds_read_b128 v[196:199], v200 offset:56320
	s_add_i32 s29, s29, s48
	v_lshl_add_u64 v[176:177], s[46:47], 0, v[202:203]
	s_mov_b32 m0, s29
	s_add_u32 s46, s46, 0x30000
	global_load_lds_dwordx4 v[176:177], off
	s_addc_u32 s47, s47, 0
	s_add_i32 m0, s29, 0x2000
	s_add_u32 s44, s44, 0x60080
	s_addc_u32 s45, s45, 0
	v_lshl_add_u64 v[176:177], s[46:47], 0, v[202:203]
	global_load_lds_dwordx4 v[176:177], off
	s_add_i32 s29, s76, s48
	v_lshl_add_u64 v[176:177], s[44:45], 0, v[202:203]
	s_add_u32 s44, s44, 0x30000
	s_mov_b32 m0, s29
	s_addc_u32 s45, s45, 0
	global_load_lds_dwordx4 v[176:177], off
	s_add_i32 m0, s29, 0x2000
	v_lshl_add_u64 v[176:177], s[44:45], 0, v[202:203]
	global_load_lds_dwordx4 v[176:177], off
	s_mov_b32 m0, s53
	v_lshl_add_u64 v[176:177], s[10:11], 0, v[158:159]
	s_add_u32 s10, s10, 0x40000
	s_addc_u32 s11, s11, 0
	global_load_lds_dwordx4 v[176:177], off
	s_mov_b32 m0, s54
	v_lshl_add_u64 v[176:177], s[10:11], 0, v[158:159]
	global_load_lds_dwordx4 v[176:177], off
	s_waitcnt vmcnt(8)
	s_waitcnt lgkmcnt(0)
	s_barrier
	s_setprio 1
	s_waitcnt lgkmcnt(0)
	v_mfma_i32_16x16x64_i8 v[62:65], v[130:133], v[164:167], v[62:65]
	v_mfma_i32_16x16x64_i8 v[58:61], v[138:141], v[164:167], v[58:61]
	v_mfma_i32_16x16x64_i8 v[54:57], v[130:133], v[172:175], v[54:57]
	v_mfma_i32_16x16x64_i8 v[50:53], v[138:141], v[172:175], v[50:53]
	v_mfma_i32_16x16x64_i8 v[38:41], v[130:133], v[184:187], v[38:41]
	v_mfma_i32_16x16x64_i8 v[34:37], v[138:141], v[184:187], v[34:37]
	v_mfma_i32_16x16x64_i8 v[14:17], v[130:133], v[192:195], v[14:17]
	v_mfma_i32_16x16x64_i8 v[10:13], v[138:141], v[192:195], v[10:13]
	v_mfma_i32_16x16x64_i8 v[62:65], v[134:137], v[168:171], v[62:65]
	v_mfma_i32_16x16x64_i8 v[58:61], v[142:145], v[168:171], v[58:61]
	v_mfma_i32_16x16x64_i8 v[54:57], v[134:137], v[180:183], v[54:57]
	v_mfma_i32_16x16x64_i8 v[50:53], v[142:145], v[180:183], v[50:53]
	v_mfma_i32_16x16x64_i8 v[38:41], v[134:137], v[188:191], v[38:41]
	v_mfma_i32_16x16x64_i8 v[34:37], v[142:145], v[188:191], v[34:37]
	v_mfma_i32_16x16x64_i8 v[14:17], v[134:137], v[196:199], v[14:17]
	v_mfma_i32_16x16x64_i8 v[10:13], v[142:145], v[196:199], v[10:13]
	v_mfma_i32_16x16x64_i8 v[46:49], v[146:149], v[164:167], v[46:49]
	v_mfma_i32_16x16x64_i8 v[42:45], v[154:157], v[164:167], v[42:45]
	v_mfma_i32_16x16x64_i8 v[30:33], v[146:149], v[172:175], v[30:33]
	v_mfma_i32_16x16x64_i8 v[26:29], v[154:157], v[172:175], v[26:29]
	v_mfma_i32_16x16x64_i8 v[22:25], v[146:149], v[184:187], v[22:25]
	v_mfma_i32_16x16x64_i8 v[18:21], v[154:157], v[184:187], v[18:21]
	v_mfma_i32_16x16x64_i8 v[6:9], v[146:149], v[192:195], v[6:9]
	v_mfma_i32_16x16x64_i8 v[2:5], v[154:157], v[192:195], v[2:5]
	v_mfma_i32_16x16x64_i8 v[46:49], v[150:153], v[168:171], v[46:49]
	v_mfma_i32_16x16x64_i8 v[42:45], v[160:163], v[168:171], v[42:45]
	v_mfma_i32_16x16x64_i8 v[30:33], v[150:153], v[180:183], v[30:33]
	v_mfma_i32_16x16x64_i8 v[26:29], v[160:163], v[180:183], v[26:29]
	v_mfma_i32_16x16x64_i8 v[22:25], v[150:153], v[188:191], v[22:25]
	v_mfma_i32_16x16x64_i8 v[18:21], v[160:163], v[188:191], v[18:21]
	v_mfma_i32_16x16x64_i8 v[6:9], v[150:153], v[196:199], v[6:9]
	v_mfma_i32_16x16x64_i8 v[2:5], v[160:163], v[196:199], v[2:5]
	s_setprio 0
	s_barrier
	s_add_u32 s74, s74, 0x100
	s_addc_u32 s75, s75, 0
	s_add_u32 s72, s72, 0x100
	s_addc_u32 s73, s73, 0
	s_cmp_ge_i32 s28, s69
	s_mov_b32 s10, s28
	s_cbranch_scc0 .LBB0_1026
	s_and_b64 vcc, exec, s[18:19]
	s_cbranch_vccz .LBB0_1029
	s_barrier

.LBB0_1096:
	s_cmp_eq_u32 s29, 28
	s_cselect_b32 s56, s50, s7
	s_cselect_b32 s57, s51, s21
	s_cselect_b32 s54, s52, s27
	s_cselect_b32 s55, s53, s28
	s_add_u32 s48, s56, 0x80
	s_addc_u32 s49, s57, 0
	s_add_i32 s76, 0, 0x10000
	s_add_i32 s77, 0, 0x14000
	v_add_u32_e32 v142, s76, v207
	v_add_u32_e32 v158, s77, v207
	s_waitcnt lgkmcnt(0)
	ds_read_b128 v[130:133], v142
	ds_read_b128 v[134:137], v142 offset:1024
	ds_read_b128 v[138:141], v142 offset:2048
	ds_read_b128 v[142:145], v142 offset:3072
	ds_read_b128 v[146:149], v158
	ds_read_b128 v[150:153], v158 offset:1024
	ds_read_b128 v[154:157], v158 offset:2048
	ds_read_b128 v[158:161], v158 offset:3072
	s_mov_b64 s[74:75], s[46:47]
	ds_read_b128 v[162:165], v237
	ds_read_b128 v[166:169], v237 offset:1024
	ds_read_b128 v[170:173], v237 offset:2048
	ds_read_b128 v[174:177], v237 offset:3072
	ds_read_b128 v[178:181], v237 offset:4096
	ds_read_b128 v[182:185], v237 offset:5120
	ds_read_b128 v[188:191], v237 offset:6144
	ds_read_b128 v[192:195], v237 offset:7168
	s_add_i32 m0, s62, 0xc000
	v_lshl_add_u64 v[196:197], s[74:75], 0, v[186:187]
	s_add_u32 s74, s74, 0x40000
	s_addc_u32 s75, s75, 0
	global_load_lds_dwordx4 v[196:197], off
	s_add_i32 m0, s62, 0xe000
	v_lshl_add_u64 v[196:197], s[74:75], 0, v[186:187]
	global_load_lds_dwordx4 v[196:197], off
	s_waitcnt vmcnt(8)
	s_waitcnt lgkmcnt(0)
	s_barrier
	s_setprio 1
	s_waitcnt lgkmcnt(0)
	v_mfma_f32_16x16x32_bf16 v[2:5], v[130:133], v[162:165], v[2:5]
	v_mfma_f32_16x16x32_bf16 v[6:9], v[138:141], v[162:165], v[6:9]
	v_mfma_f32_16x16x32_bf16 v[14:17], v[130:133], v[170:173], v[14:17]
	v_mfma_f32_16x16x32_bf16 v[22:25], v[138:141], v[170:173], v[22:25]
	v_mfma_f32_16x16x32_bf16 v[30:33], v[130:133], v[178:181], v[30:33]
	v_mfma_f32_16x16x32_bf16 v[38:41], v[138:141], v[178:181], v[38:41]
	v_mfma_f32_16x16x32_bf16 v[46:49], v[130:133], v[188:191], v[46:49]
	v_mfma_f32_16x16x32_bf16 v[54:57], v[138:141], v[188:191], v[54:57]
	v_mfma_f32_16x16x32_bf16 v[2:5], v[134:137], v[166:169], v[2:5]
	v_mfma_f32_16x16x32_bf16 v[6:9], v[142:145], v[166:169], v[6:9]
	v_mfma_f32_16x16x32_bf16 v[14:17], v[134:137], v[174:177], v[14:17]
	v_mfma_f32_16x16x32_bf16 v[22:25], v[142:145], v[174:177], v[22:25]
	v_mfma_f32_16x16x32_bf16 v[30:33], v[134:137], v[182:185], v[30:33]
	v_mfma_f32_16x16x32_bf16 v[38:41], v[142:145], v[182:185], v[38:41]
	v_mfma_f32_16x16x32_bf16 v[46:49], v[134:137], v[192:195], v[46:49]
	v_mfma_f32_16x16x32_bf16 v[54:57], v[142:145], v[192:195], v[54:57]
	v_mfma_f32_16x16x32_bf16 v[10:13], v[146:149], v[162:165], v[10:13]
	v_mfma_f32_16x16x32_bf16 v[18:21], v[154:157], v[162:165], v[18:21]
	v_mfma_f32_16x16x32_bf16 v[26:29], v[146:149], v[170:173], v[26:29]
	v_mfma_f32_16x16x32_bf16 v[34:37], v[154:157], v[170:173], v[34:37]
	v_mfma_f32_16x16x32_bf16 v[42:45], v[146:149], v[178:181], v[42:45]
	v_mfma_f32_16x16x32_bf16 v[50:53], v[154:157], v[178:181], v[50:53]
	v_mfma_f32_16x16x32_bf16 v[58:61], v[146:149], v[188:191], v[58:61]
	v_mfma_f32_16x16x32_bf16 v[62:65], v[154:157], v[188:191], v[62:65]
	v_mfma_f32_16x16x32_bf16 v[10:13], v[150:153], v[166:169], v[10:13]
	v_mfma_f32_16x16x32_bf16 v[18:21], v[158:161], v[166:169], v[18:21]
	v_mfma_f32_16x16x32_bf16 v[26:29], v[150:153], v[174:177], v[26:29]
	v_mfma_f32_16x16x32_bf16 v[34:37], v[158:161], v[174:177], v[34:37]
	v_mfma_f32_16x16x32_bf16 v[42:45], v[150:153], v[182:185], v[42:45]
	v_mfma_f32_16x16x32_bf16 v[50:53], v[158:161], v[182:185], v[50:53]
	v_mfma_f32_16x16x32_bf16 v[58:61], v[150:153], v[192:195], v[58:61]
	v_mfma_f32_16x16x32_bf16 v[62:65], v[158:161], v[192:195], v[62:65]
	s_setprio 0
	s_barrier
	s_mov_b64 s[74:75], s[54:55]
	ds_read_b128 v[162:165], v237 offset:16384
	ds_read_b128 v[166:169], v237 offset:17408
	ds_read_b128 v[170:173], v237 offset:18432
	ds_read_b128 v[174:177], v237 offset:19456
	ds_read_b128 v[178:181], v237 offset:20480
	ds_read_b128 v[182:185], v237 offset:21504
	ds_read_b128 v[188:191], v237 offset:22528
	ds_read_b128 v[192:195], v237 offset:23552
	s_add_i32 s76, s76, s61
	v_lshl_add_u64 v[196:197], s[74:75], 0, v[202:203]
	s_add_u32 s74, s74, 0x40000
	s_mov_b32 m0, s76
	s_addc_u32 s75, s75, 0
	global_load_lds_dwordx4 v[196:197], off
	s_add_i32 m0, s76, 0x2000
	v_lshl_add_u64 v[196:197], s[74:75], 0, v[202:203]
	s_add_u32 s74, s54, 0x80000
	s_addc_u32 s75, s55, 0
	global_load_lds_dwordx4 v[196:197], off
	s_add_i32 s76, s77, s61
	v_lshl_add_u64 v[196:197], s[74:75], 0, v[202:203]
	s_add_u32 s74, s74, 0x40000
	s_mov_b32 m0, s76
	s_addc_u32 s75, s75, 0
	global_load_lds_dwordx4 v[196:197], off
	s_add_i32 m0, s76, 0x2000
	v_lshl_add_u64 v[196:197], s[74:75], 0, v[202:203]
	s_mov_b64 s[74:75], s[56:57]
	global_load_lds_dwordx4 v[196:197], off
	s_mov_b32 m0, s62
	v_lshl_add_u64 v[196:197], s[74:75], 0, v[186:187]
	s_add_u32 s74, s74, 0x40000
	s_addc_u32 s75, s75, 0
	global_load_lds_dwordx4 v[196:197], off
	s_mov_b32 m0, s63
	v_lshl_add_u64 v[196:197], s[74:75], 0, v[186:187]
	global_load_lds_dwordx4 v[196:197], off
	s_waitcnt vmcnt(8)
	s_waitcnt lgkmcnt(0)
	s_barrier
	s_setprio 1
	s_waitcnt lgkmcnt(0)
	v_mfma_f32_16x16x32_bf16 v[66:69], v[130:133], v[162:165], v[66:69]
	v_mfma_f32_16x16x32_bf16 v[70:73], v[138:141], v[162:165], v[70:73]
	v_mfma_f32_16x16x32_bf16 v[74:77], v[130:133], v[170:173], v[74:77]
	v_mfma_f32_16x16x32_bf16 v[78:81], v[138:141], v[170:173], v[78:81]
	v_mfma_f32_16x16x32_bf16 v[86:89], v[130:133], v[178:181], v[86:89]
	v_mfma_f32_16x16x32_bf16 v[94:97], v[138:141], v[178:181], v[94:97]
	v_mfma_f32_16x16x32_bf16 v[102:105], v[130:133], v[188:191], v[102:105]
	v_mfma_f32_16x16x32_bf16 v[110:113], v[138:141], v[188:191], v[110:113]
	v_mfma_f32_16x16x32_bf16 v[66:69], v[134:137], v[166:169], v[66:69]
	v_mfma_f32_16x16x32_bf16 v[70:73], v[142:145], v[166:169], v[70:73]
	v_mfma_f32_16x16x32_bf16 v[74:77], v[134:137], v[174:177], v[74:77]
	v_mfma_f32_16x16x32_bf16 v[78:81], v[142:145], v[174:177], v[78:81]
	v_mfma_f32_16x16x32_bf16 v[86:89], v[134:137], v[182:185], v[86:89]
	v_mfma_f32_16x16x32_bf16 v[94:97], v[142:145], v[182:185], v[94:97]
	v_mfma_f32_16x16x32_bf16 v[102:105], v[134:137], v[192:195], v[102:105]
	v_mfma_f32_16x16x32_bf16 v[110:113], v[142:145], v[192:195], v[110:113]
	v_mfma_f32_16x16x32_bf16 v[82:85], v[146:149], v[162:165], v[82:85]
	v_mfma_f32_16x16x32_bf16 v[90:93], v[154:157], v[162:165], v[90:93]
	v_mfma_f32_16x16x32_bf16 v[98:101], v[146:149], v[170:173], v[98:101]
	v_mfma_f32_16x16x32_bf16 v[106:109], v[154:157], v[170:173], v[106:109]
	v_mfma_f32_16x16x32_bf16 v[114:117], v[146:149], v[178:181], v[114:117]
	v_mfma_f32_16x16x32_bf16 v[118:121], v[154:157], v[178:181], v[118:121]
	v_mfma_f32_16x16x32_bf16 v[122:125], v[146:149], v[188:191], v[122:125]
	v_mfma_f32_16x16x32_bf16 v[126:129], v[154:157], v[188:191], v[126:129]
	v_mfma_f32_16x16x32_bf16 v[82:85], v[150:153], v[166:169], v[82:85]
	v_mfma_f32_16x16x32_bf16 v[90:93], v[158:161], v[166:169], v[90:93]
	v_mfma_f32_16x16x32_bf16 v[98:101], v[150:153], v[174:177], v[98:101]
	v_mfma_f32_16x16x32_bf16 v[106:109], v[158:161], v[174:177], v[106:109]
	v_mfma_f32_16x16x32_bf16 v[114:117], v[150:153], v[182:185], v[114:117]
	v_mfma_f32_16x16x32_bf16 v[118:121], v[158:161], v[182:185], v[118:121]
	v_mfma_f32_16x16x32_bf16 v[122:125], v[150:153], v[192:195], v[122:125]
	v_mfma_f32_16x16x32_bf16 v[126:129], v[158:161], v[192:195], v[126:129]
	s_setprio 0
	s_barrier
	s_add_i32 s74, 0, 0x18000
	s_add_i32 s75, 0, 0x1c000
	v_add_u32_e32 v142, s74, v207
	v_add_u32_e32 v158, s75, v207
	ds_read_b128 v[130:133], v142
	ds_read_b128 v[134:137], v142 offset:1024
	ds_read_b128 v[138:141], v142 offset:2048
	ds_read_b128 v[142:145], v142 offset:3072
	ds_read_b128 v[146:149], v158
	ds_read_b128 v[150:153], v158 offset:1024
	ds_read_b128 v[154:157], v158 offset:2048
	ds_read_b128 v[158:161], v158 offset:3072
	s_add_u32 s56, s56, 0x80000
	s_addc_u32 s57, s57, 0
	ds_read_b128 v[162:165], v237 offset:32768
	ds_read_b128 v[166:169], v237 offset:33792
	ds_read_b128 v[170:173], v237 offset:34816
	ds_read_b128 v[174:177], v237 offset:35840
	ds_read_b128 v[178:181], v237 offset:36864
	ds_read_b128 v[182:185], v237 offset:37888
	ds_read_b128 v[188:191], v237 offset:38912
	ds_read_b128 v[192:195], v237 offset:39936
	s_mov_b32 m0, s64
	v_lshl_add_u64 v[196:197], s[56:57], 0, v[186:187]
	s_add_u32 s56, s56, 0x40000
	s_addc_u32 s57, s57, 0
	global_load_lds_dwordx4 v[196:197], off
	s_mov_b32 m0, s65
	v_lshl_add_u64 v[196:197], s[56:57], 0, v[186:187]
	global_load_lds_dwordx4 v[196:197], off
	s_waitcnt vmcnt(8)
	s_waitcnt lgkmcnt(0)
	s_barrier
	s_setprio 1
	s_waitcnt lgkmcnt(0)
	v_mfma_f32_16x16x32_bf16 v[2:5], v[130:133], v[162:165], v[2:5]
	v_mfma_f32_16x16x32_bf16 v[6:9], v[138:141], v[162:165], v[6:9]
	v_mfma_f32_16x16x32_bf16 v[14:17], v[130:133], v[170:173], v[14:17]
	v_mfma_f32_16x16x32_bf16 v[22:25], v[138:141], v[170:173], v[22:25]
	v_mfma_f32_16x16x32_bf16 v[30:33], v[130:133], v[178:181], v[30:33]
	v_mfma_f32_16x16x32_bf16 v[38:41], v[138:141], v[178:181], v[38:41]
	v_mfma_f32_16x16x32_bf16 v[46:49], v[130:133], v[188:191], v[46:49]
	v_mfma_f32_16x16x32_bf16 v[54:57], v[138:141], v[188:191], v[54:57]
	v_mfma_f32_16x16x32_bf16 v[2:5], v[134:137], v[166:169], v[2:5]
	v_mfma_f32_16x16x32_bf16 v[6:9], v[142:145], v[166:169], v[6:9]
	v_mfma_f32_16x16x32_bf16 v[14:17], v[134:137], v[174:177], v[14:17]
	v_mfma_f32_16x16x32_bf16 v[22:25], v[142:145], v[174:177], v[22:25]
	v_mfma_f32_16x16x32_bf16 v[30:33], v[134:137], v[182:185], v[30:33]
	v_mfma_f32_16x16x32_bf16 v[38:41], v[142:145], v[182:185], v[38:41]
	v_mfma_f32_16x16x32_bf16 v[46:49], v[134:137], v[192:195], v[46:49]
	v_mfma_f32_16x16x32_bf16 v[54:57], v[142:145], v[192:195], v[54:57]
	v_mfma_f32_16x16x32_bf16 v[10:13], v[146:149], v[162:165], v[10:13]
	v_mfma_f32_16x16x32_bf16 v[18:21], v[154:157], v[162:165], v[18:21]
	v_mfma_f32_16x16x32_bf16 v[26:29], v[146:149], v[170:173], v[26:29]
	v_mfma_f32_16x16x32_bf16 v[34:37], v[154:157], v[170:173], v[34:37]
	v_mfma_f32_16x16x32_bf16 v[42:45], v[146:149], v[178:181], v[42:45]
	v_mfma_f32_16x16x32_bf16 v[50:53], v[154:157], v[178:181], v[50:53]
	v_mfma_f32_16x16x32_bf16 v[58:61], v[146:149], v[188:191], v[58:61]
	v_mfma_f32_16x16x32_bf16 v[62:65], v[154:157], v[188:191], v[62:65]
	v_mfma_f32_16x16x32_bf16 v[10:13], v[150:153], v[166:169], v[10:13]
	v_mfma_f32_16x16x32_bf16 v[18:21], v[158:161], v[166:169], v[18:21]
	v_mfma_f32_16x16x32_bf16 v[26:29], v[150:153], v[174:177], v[26:29]
	v_mfma_f32_16x16x32_bf16 v[34:37], v[158:161], v[174:177], v[34:37]
	v_mfma_f32_16x16x32_bf16 v[42:45], v[150:153], v[182:185], v[42:45]
	v_mfma_f32_16x16x32_bf16 v[50:53], v[158:161], v[182:185], v[50:53]
	v_mfma_f32_16x16x32_bf16 v[58:61], v[150:153], v[192:195], v[58:61]
	v_mfma_f32_16x16x32_bf16 v[62:65], v[158:161], v[192:195], v[62:65]
	s_setprio 0
	s_barrier
	s_add_u32 s56, s54, 0x80
	s_addc_u32 s57, s55, 0
	ds_read_b128 v[162:165], v237 offset:49152
	ds_read_b128 v[166:169], v237 offset:50176
	ds_read_b128 v[170:173], v237 offset:51200
	ds_read_b128 v[174:177], v237 offset:52224
	ds_read_b128 v[178:181], v237 offset:53248
	ds_read_b128 v[182:185], v237 offset:54272
	ds_read_b128 v[188:191], v237 offset:55296
	ds_read_b128 v[192:195], v237 offset:56320
	s_add_i32 s74, s74, s61
	v_lshl_add_u64 v[196:197], s[56:57], 0, v[202:203]
	s_mov_b32 m0, s74
	s_add_u32 s56, s56, 0x40000
	global_load_lds_dwordx4 v[196:197], off
	s_addc_u32 s57, s57, 0
	s_add_i32 m0, s74, 0x2000
	s_add_u32 s54, s54, 0x80080
	s_addc_u32 s55, s55, 0
	v_lshl_add_u64 v[196:197], s[56:57], 0, v[202:203]
	global_load_lds_dwordx4 v[196:197], off
	s_add_i32 s56, s75, s61
	v_lshl_add_u64 v[196:197], s[54:55], 0, v[202:203]
	s_add_u32 s54, s54, 0x40000
	s_mov_b32 m0, s56
	s_addc_u32 s55, s55, 0
	global_load_lds_dwordx4 v[196:197], off
	s_add_i32 m0, s56, 0x2000
	v_lshl_add_u64 v[196:197], s[54:55], 0, v[202:203]
	global_load_lds_dwordx4 v[196:197], off
	s_mov_b32 m0, s66
	v_lshl_add_u64 v[196:197], s[48:49], 0, v[186:187]
	s_add_u32 s48, s48, 0x40000
	s_addc_u32 s49, s49, 0
	global_load_lds_dwordx4 v[196:197], off
	s_mov_b32 m0, s67
	v_lshl_add_u64 v[196:197], s[48:49], 0, v[186:187]
	global_load_lds_dwordx4 v[196:197], off
	s_waitcnt vmcnt(8)
	s_waitcnt lgkmcnt(0)
	s_barrier
	s_setprio 1
	s_waitcnt lgkmcnt(0)
	v_mfma_f32_16x16x32_bf16 v[66:69], v[130:133], v[162:165], v[66:69]
	v_mfma_f32_16x16x32_bf16 v[70:73], v[138:141], v[162:165], v[70:73]
	v_mfma_f32_16x16x32_bf16 v[74:77], v[130:133], v[170:173], v[74:77]
	v_mfma_f32_16x16x32_bf16 v[78:81], v[138:141], v[170:173], v[78:81]
	v_mfma_f32_16x16x32_bf16 v[86:89], v[130:133], v[178:181], v[86:89]
	v_mfma_f32_16x16x32_bf16 v[94:97], v[138:141], v[178:181], v[94:97]
	v_mfma_f32_16x16x32_bf16 v[102:105], v[130:133], v[188:191], v[102:105]
	v_mfma_f32_16x16x32_bf16 v[110:113], v[138:141], v[188:191], v[110:113]
	v_mfma_f32_16x16x32_bf16 v[66:69], v[134:137], v[166:169], v[66:69]
	v_mfma_f32_16x16x32_bf16 v[70:73], v[142:145], v[166:169], v[70:73]
	v_mfma_f32_16x16x32_bf16 v[74:77], v[134:137], v[174:177], v[74:77]
	v_mfma_f32_16x16x32_bf16 v[78:81], v[142:145], v[174:177], v[78:81]
	v_mfma_f32_16x16x32_bf16 v[86:89], v[134:137], v[182:185], v[86:89]
	v_mfma_f32_16x16x32_bf16 v[94:97], v[142:145], v[182:185], v[94:97]
	v_mfma_f32_16x16x32_bf16 v[102:105], v[134:137], v[192:195], v[102:105]
	v_mfma_f32_16x16x32_bf16 v[110:113], v[142:145], v[192:195], v[110:113]
	v_mfma_f32_16x16x32_bf16 v[82:85], v[146:149], v[162:165], v[82:85]
	v_mfma_f32_16x16x32_bf16 v[90:93], v[154:157], v[162:165], v[90:93]
	v_mfma_f32_16x16x32_bf16 v[98:101], v[146:149], v[170:173], v[98:101]
	v_mfma_f32_16x16x32_bf16 v[106:109], v[154:157], v[170:173], v[106:109]
	v_mfma_f32_16x16x32_bf16 v[114:117], v[146:149], v[178:181], v[114:117]
	v_mfma_f32_16x16x32_bf16 v[118:121], v[154:157], v[178:181], v[118:121]
	v_mfma_f32_16x16x32_bf16 v[122:125], v[146:149], v[188:191], v[122:125]
	v_mfma_f32_16x16x32_bf16 v[126:129], v[154:157], v[188:191], v[126:129]
	v_mfma_f32_16x16x32_bf16 v[82:85], v[150:153], v[166:169], v[82:85]
	v_mfma_f32_16x16x32_bf16 v[90:93], v[158:161], v[166:169], v[90:93]
	v_mfma_f32_16x16x32_bf16 v[98:101], v[150:153], v[174:177], v[98:101]
	v_mfma_f32_16x16x32_bf16 v[106:109], v[158:161], v[174:177], v[106:109]
	v_mfma_f32_16x16x32_bf16 v[114:117], v[150:153], v[182:185], v[114:117]
	v_mfma_f32_16x16x32_bf16 v[118:121], v[158:161], v[182:185], v[118:121]
	v_mfma_f32_16x16x32_bf16 v[122:125], v[150:153], v[192:195], v[122:125]
	v_mfma_f32_16x16x32_bf16 v[126:129], v[158:161], v[192:195], v[126:129]
	s_setprio 0
	s_barrier
	s_add_i32 s29, s29, 2
	s_add_u32 s7, s7, 0x100
	s_addc_u32 s21, s21, 0
	s_add_u32 s27, s27, 0x100
	s_addc_u32 s28, s28, 0
	s_add_u32 s46, s46, 0x100
	s_addc_u32 s47, s47, 0
	s_cmp_gt_u32 s29, 29
	s_cbranch_scc0 .LBB0_1096
	s_and_b64 vcc, exec, s[18:19]
	s_cbranch_vccz .LBB0_1099
	s_barrier

.LBB0_1214:
	s_cmp_eq_u32 s65, 12
	s_cselect_b32 s50, s42, s23
	s_cselect_b32 s51, s43, s62
	s_cselect_b32 s48, s44, s63
	s_cselect_b32 s49, s45, s64
	s_add_u32 s46, s50, 0x80
	s_addc_u32 s47, s51, 0
	s_add_i32 s68, 0, 0x10000
	s_add_i32 s69, 0, 0x14000
	v_add_u32_e32 v142, s68, v208
	v_add_u32_e32 v158, s69, v208
	ds_read_b128 v[130:133], v142
	ds_read_b128 v[134:137], v142 offset:1024
	ds_read_b128 v[138:141], v142 offset:2048
	ds_read_b128 v[142:145], v142 offset:3072
	ds_read_b128 v[146:149], v158
	ds_read_b128 v[150:153], v158 offset:1024
	ds_read_b128 v[154:157], v158 offset:2048
	ds_read_b128 v[158:161], v158 offset:3072
	s_add_u32 s66, s23, 0x7ff80
	s_addc_u32 s67, s62, 0
	ds_read_b128 v[162:165], v210
	ds_read_b128 v[166:169], v210 offset:1024
	ds_read_b128 v[170:173], v210 offset:2048
	ds_read_b128 v[174:177], v210 offset:3072
	ds_read_b128 v[180:183], v210 offset:4096
	ds_read_b128 v[184:187], v210 offset:5120
	ds_read_b128 v[188:191], v210 offset:6144
	ds_read_b128 v[192:195], v210 offset:7168
	s_add_i32 m0, s52, 0xc000
	v_lshl_add_u64 v[196:197], s[66:67], 0, v[178:179]
	s_add_u32 s66, s66, 0x40000
	s_addc_u32 s67, s67, 0
	global_load_lds_dwordx4 v[196:197], off
	s_add_i32 m0, s52, 0xe000
	v_lshl_add_u64 v[196:197], s[66:67], 0, v[178:179]
	global_load_lds_dwordx4 v[196:197], off
	s_waitcnt vmcnt(8)
	s_waitcnt lgkmcnt(0)
	s_barrier
	s_setprio 1
	s_waitcnt lgkmcnt(0)
	v_mfma_i32_16x16x64_i8 v[126:129], v[130:133], v[162:165], v[126:129]
	v_mfma_i32_16x16x64_i8 v[118:121], v[138:141], v[162:165], v[118:121]
	v_mfma_i32_16x16x64_i8 v[110:113], v[130:133], v[170:173], v[110:113]
	v_mfma_i32_16x16x64_i8 v[102:105], v[138:141], v[170:173], v[102:105]
	v_mfma_i32_16x16x64_i8 v[94:97], v[130:133], v[180:183], v[94:97]
	v_mfma_i32_16x16x64_i8 v[86:89], v[138:141], v[180:183], v[86:89]
	v_mfma_i32_16x16x64_i8 v[78:81], v[130:133], v[188:191], v[78:81]
	v_mfma_i32_16x16x64_i8 v[70:73], v[138:141], v[188:191], v[70:73]
	v_mfma_i32_16x16x64_i8 v[126:129], v[134:137], v[166:169], v[126:129]
	v_mfma_i32_16x16x64_i8 v[118:121], v[142:145], v[166:169], v[118:121]
	v_mfma_i32_16x16x64_i8 v[110:113], v[134:137], v[174:177], v[110:113]
	v_mfma_i32_16x16x64_i8 v[102:105], v[142:145], v[174:177], v[102:105]
	v_mfma_i32_16x16x64_i8 v[94:97], v[134:137], v[184:187], v[94:97]
	v_mfma_i32_16x16x64_i8 v[86:89], v[142:145], v[184:187], v[86:89]
	v_mfma_i32_16x16x64_i8 v[78:81], v[134:137], v[192:195], v[78:81]
	v_mfma_i32_16x16x64_i8 v[70:73], v[142:145], v[192:195], v[70:73]
	v_mfma_i32_16x16x64_i8 v[122:125], v[146:149], v[162:165], v[122:125]
	v_mfma_i32_16x16x64_i8 v[114:117], v[154:157], v[162:165], v[114:117]
	v_mfma_i32_16x16x64_i8 v[106:109], v[146:149], v[170:173], v[106:109]
	v_mfma_i32_16x16x64_i8 v[98:101], v[154:157], v[170:173], v[98:101]
	v_mfma_i32_16x16x64_i8 v[90:93], v[146:149], v[180:183], v[90:93]
	v_mfma_i32_16x16x64_i8 v[82:85], v[154:157], v[180:183], v[82:85]
	v_mfma_i32_16x16x64_i8 v[74:77], v[146:149], v[188:191], v[74:77]
	v_mfma_i32_16x16x64_i8 v[66:69], v[154:157], v[188:191], v[66:69]
	v_mfma_i32_16x16x64_i8 v[122:125], v[150:153], v[166:169], v[122:125]
	v_mfma_i32_16x16x64_i8 v[114:117], v[158:161], v[166:169], v[114:117]
	v_mfma_i32_16x16x64_i8 v[106:109], v[150:153], v[174:177], v[106:109]
	v_mfma_i32_16x16x64_i8 v[98:101], v[158:161], v[174:177], v[98:101]
	v_mfma_i32_16x16x64_i8 v[90:93], v[150:153], v[184:187], v[90:93]
	v_mfma_i32_16x16x64_i8 v[82:85], v[158:161], v[184:187], v[82:85]
	v_mfma_i32_16x16x64_i8 v[74:77], v[150:153], v[192:195], v[74:77]
	v_mfma_i32_16x16x64_i8 v[66:69], v[158:161], v[192:195], v[66:69]
	s_setprio 0
	s_barrier
	s_mov_b64 s[66:67], s[48:49]
	ds_read_b128 v[162:165], v210 offset:16384
	ds_read_b128 v[166:169], v210 offset:17408
	ds_read_b128 v[170:173], v210 offset:18432
	ds_read_b128 v[174:177], v210 offset:19456
	ds_read_b128 v[180:183], v210 offset:20480
	ds_read_b128 v[184:187], v210 offset:21504
	ds_read_b128 v[188:191], v210 offset:22528
	ds_read_b128 v[192:195], v210 offset:23552
	s_add_i32 s68, s68, s31
	v_lshl_add_u64 v[196:197], s[66:67], 0, v[202:203]
	s_add_u32 s66, s66, 0x20000
	s_mov_b32 m0, s68
	s_addc_u32 s67, s67, 0
	global_load_lds_dwordx4 v[196:197], off
	s_add_i32 m0, s68, 0x2000
	v_lshl_add_u64 v[196:197], s[66:67], 0, v[202:203]
	s_add_u32 s66, s48, 0x40000
	s_addc_u32 s67, s49, 0
	global_load_lds_dwordx4 v[196:197], off
	s_add_i32 s68, s69, s31
	v_lshl_add_u64 v[196:197], s[66:67], 0, v[202:203]
	s_add_u32 s66, s66, 0x20000
	s_mov_b32 m0, s68
	s_addc_u32 s67, s67, 0
	global_load_lds_dwordx4 v[196:197], off
	s_add_i32 m0, s68, 0x2000
	v_lshl_add_u64 v[196:197], s[66:67], 0, v[202:203]
	s_mov_b64 s[66:67], s[50:51]
	global_load_lds_dwordx4 v[196:197], off
	s_mov_b32 m0, s52
	v_lshl_add_u64 v[196:197], s[66:67], 0, v[178:179]
	s_add_u32 s66, s66, 0x40000
	s_addc_u32 s67, s67, 0
	global_load_lds_dwordx4 v[196:197], off
	s_mov_b32 m0, s53
	v_lshl_add_u64 v[196:197], s[66:67], 0, v[178:179]
	global_load_lds_dwordx4 v[196:197], off
	s_waitcnt vmcnt(8)
	s_waitcnt lgkmcnt(0)
	s_barrier
	s_setprio 1
	s_waitcnt lgkmcnt(0)
	v_mfma_i32_16x16x64_i8 v[62:65], v[130:133], v[162:165], v[62:65]
	v_mfma_i32_16x16x64_i8 v[54:57], v[138:141], v[162:165], v[54:57]
	v_mfma_i32_16x16x64_i8 v[46:49], v[130:133], v[170:173], v[46:49]
	v_mfma_i32_16x16x64_i8 v[38:41], v[138:141], v[170:173], v[38:41]
	v_mfma_i32_16x16x64_i8 v[30:33], v[130:133], v[180:183], v[30:33]
	v_mfma_i32_16x16x64_i8 v[22:25], v[138:141], v[180:183], v[22:25]
	v_mfma_i32_16x16x64_i8 v[14:17], v[130:133], v[188:191], v[14:17]
	v_mfma_i32_16x16x64_i8 v[6:9], v[138:141], v[188:191], v[6:9]
	v_mfma_i32_16x16x64_i8 v[62:65], v[134:137], v[166:169], v[62:65]
	v_mfma_i32_16x16x64_i8 v[54:57], v[142:145], v[166:169], v[54:57]
	v_mfma_i32_16x16x64_i8 v[46:49], v[134:137], v[174:177], v[46:49]
	v_mfma_i32_16x16x64_i8 v[38:41], v[142:145], v[174:177], v[38:41]
	v_mfma_i32_16x16x64_i8 v[30:33], v[134:137], v[184:187], v[30:33]
	v_mfma_i32_16x16x64_i8 v[22:25], v[142:145], v[184:187], v[22:25]
	v_mfma_i32_16x16x64_i8 v[14:17], v[134:137], v[192:195], v[14:17]
	v_mfma_i32_16x16x64_i8 v[6:9], v[142:145], v[192:195], v[6:9]
	v_mfma_i32_16x16x64_i8 v[58:61], v[146:149], v[162:165], v[58:61]
	v_mfma_i32_16x16x64_i8 v[50:53], v[154:157], v[162:165], v[50:53]
	v_mfma_i32_16x16x64_i8 v[42:45], v[146:149], v[170:173], v[42:45]
	v_mfma_i32_16x16x64_i8 v[34:37], v[154:157], v[170:173], v[34:37]
	v_mfma_i32_16x16x64_i8 v[26:29], v[146:149], v[180:183], v[26:29]
	v_mfma_i32_16x16x64_i8 v[18:21], v[154:157], v[180:183], v[18:21]
	v_mfma_i32_16x16x64_i8 v[10:13], v[146:149], v[188:191], v[10:13]
	v_mfma_i32_16x16x64_i8 v[2:5], v[154:157], v[188:191], v[2:5]
	v_mfma_i32_16x16x64_i8 v[58:61], v[150:153], v[166:169], v[58:61]
	v_mfma_i32_16x16x64_i8 v[50:53], v[158:161], v[166:169], v[50:53]
	v_mfma_i32_16x16x64_i8 v[42:45], v[150:153], v[174:177], v[42:45]
	v_mfma_i32_16x16x64_i8 v[34:37], v[158:161], v[174:177], v[34:37]
	v_mfma_i32_16x16x64_i8 v[26:29], v[150:153], v[184:187], v[26:29]
	v_mfma_i32_16x16x64_i8 v[18:21], v[158:161], v[184:187], v[18:21]
	v_mfma_i32_16x16x64_i8 v[10:13], v[150:153], v[192:195], v[10:13]
	v_mfma_i32_16x16x64_i8 v[2:5], v[158:161], v[192:195], v[2:5]
	s_setprio 0
	s_barrier
	s_add_i32 s66, 0, 0x18000
	s_add_i32 s67, 0, 0x1c000
	v_add_u32_e32 v142, s66, v208
	v_add_u32_e32 v158, s67, v208
	ds_read_b128 v[130:133], v142
	ds_read_b128 v[134:137], v142 offset:1024
	ds_read_b128 v[138:141], v142 offset:2048
	ds_read_b128 v[142:145], v142 offset:3072
	ds_read_b128 v[146:149], v158
	ds_read_b128 v[150:153], v158 offset:1024
	ds_read_b128 v[154:157], v158 offset:2048
	ds_read_b128 v[158:161], v158 offset:3072
	s_add_u32 s50, s50, 0x80000
	s_addc_u32 s51, s51, 0
	ds_read_b128 v[162:165], v210 offset:32768
	ds_read_b128 v[166:169], v210 offset:33792
	ds_read_b128 v[170:173], v210 offset:34816
	ds_read_b128 v[174:177], v210 offset:35840
	ds_read_b128 v[180:183], v210 offset:36864
	ds_read_b128 v[184:187], v210 offset:37888
	ds_read_b128 v[188:191], v210 offset:38912
	ds_read_b128 v[192:195], v210 offset:39936
	s_mov_b32 m0, s54
	v_lshl_add_u64 v[196:197], s[50:51], 0, v[178:179]
	s_add_u32 s50, s50, 0x40000
	s_addc_u32 s51, s51, 0
	global_load_lds_dwordx4 v[196:197], off
	s_mov_b32 m0, s55
	v_lshl_add_u64 v[196:197], s[50:51], 0, v[178:179]
	global_load_lds_dwordx4 v[196:197], off
	s_waitcnt vmcnt(8)
	s_waitcnt lgkmcnt(0)
	s_barrier
	s_setprio 1
	s_waitcnt lgkmcnt(0)
	v_mfma_i32_16x16x64_i8 v[126:129], v[130:133], v[162:165], v[126:129]
	v_mfma_i32_16x16x64_i8 v[118:121], v[138:141], v[162:165], v[118:121]
	v_mfma_i32_16x16x64_i8 v[110:113], v[130:133], v[170:173], v[110:113]
	v_mfma_i32_16x16x64_i8 v[102:105], v[138:141], v[170:173], v[102:105]
	v_mfma_i32_16x16x64_i8 v[94:97], v[130:133], v[180:183], v[94:97]
	v_mfma_i32_16x16x64_i8 v[86:89], v[138:141], v[180:183], v[86:89]
	v_mfma_i32_16x16x64_i8 v[78:81], v[130:133], v[188:191], v[78:81]
	v_mfma_i32_16x16x64_i8 v[70:73], v[138:141], v[188:191], v[70:73]
	v_mfma_i32_16x16x64_i8 v[126:129], v[134:137], v[166:169], v[126:129]
	v_mfma_i32_16x16x64_i8 v[118:121], v[142:145], v[166:169], v[118:121]
	v_mfma_i32_16x16x64_i8 v[110:113], v[134:137], v[174:177], v[110:113]
	v_mfma_i32_16x16x64_i8 v[102:105], v[142:145], v[174:177], v[102:105]
	v_mfma_i32_16x16x64_i8 v[94:97], v[134:137], v[184:187], v[94:97]
	v_mfma_i32_16x16x64_i8 v[86:89], v[142:145], v[184:187], v[86:89]
	v_mfma_i32_16x16x64_i8 v[78:81], v[134:137], v[192:195], v[78:81]
	v_mfma_i32_16x16x64_i8 v[70:73], v[142:145], v[192:195], v[70:73]
	v_mfma_i32_16x16x64_i8 v[122:125], v[146:149], v[162:165], v[122:125]
	v_mfma_i32_16x16x64_i8 v[114:117], v[154:157], v[162:165], v[114:117]
	v_mfma_i32_16x16x64_i8 v[106:109], v[146:149], v[170:173], v[106:109]
	v_mfma_i32_16x16x64_i8 v[98:101], v[154:157], v[170:173], v[98:101]
	v_mfma_i32_16x16x64_i8 v[90:93], v[146:149], v[180:183], v[90:93]
	v_mfma_i32_16x16x64_i8 v[82:85], v[154:157], v[180:183], v[82:85]
	v_mfma_i32_16x16x64_i8 v[74:77], v[146:149], v[188:191], v[74:77]
	v_mfma_i32_16x16x64_i8 v[66:69], v[154:157], v[188:191], v[66:69]
	v_mfma_i32_16x16x64_i8 v[122:125], v[150:153], v[166:169], v[122:125]
	v_mfma_i32_16x16x64_i8 v[114:117], v[158:161], v[166:169], v[114:117]
	v_mfma_i32_16x16x64_i8 v[106:109], v[150:153], v[174:177], v[106:109]
	v_mfma_i32_16x16x64_i8 v[98:101], v[158:161], v[174:177], v[98:101]
	v_mfma_i32_16x16x64_i8 v[90:93], v[150:153], v[184:187], v[90:93]
	v_mfma_i32_16x16x64_i8 v[82:85], v[158:161], v[184:187], v[82:85]
	v_mfma_i32_16x16x64_i8 v[74:77], v[150:153], v[192:195], v[74:77]
	v_mfma_i32_16x16x64_i8 v[66:69], v[158:161], v[192:195], v[66:69]
	s_setprio 0
	s_barrier
	s_add_u32 s50, s48, 0x80
	s_addc_u32 s51, s49, 0
	ds_read_b128 v[162:165], v210 offset:49152
	ds_read_b128 v[166:169], v210 offset:50176
	ds_read_b128 v[170:173], v210 offset:51200
	ds_read_b128 v[174:177], v210 offset:52224
	ds_read_b128 v[180:183], v210 offset:53248
	ds_read_b128 v[184:187], v210 offset:54272
	ds_read_b128 v[188:191], v210 offset:55296
	ds_read_b128 v[192:195], v210 offset:56320
	s_add_i32 s66, s66, s31
	v_lshl_add_u64 v[196:197], s[50:51], 0, v[202:203]
	s_mov_b32 m0, s66
	s_add_u32 s50, s50, 0x20000
	global_load_lds_dwordx4 v[196:197], off
	s_addc_u32 s51, s51, 0
	s_add_i32 m0, s66, 0x2000
	s_add_u32 s48, s48, 0x40080
	s_addc_u32 s49, s49, 0
	v_lshl_add_u64 v[196:197], s[50:51], 0, v[202:203]
	global_load_lds_dwordx4 v[196:197], off
	s_add_i32 s50, s67, s31
	v_lshl_add_u64 v[196:197], s[48:49], 0, v[202:203]
	s_add_u32 s48, s48, 0x20000
	s_mov_b32 m0, s50
	s_addc_u32 s49, s49, 0
	global_load_lds_dwordx4 v[196:197], off
	s_add_i32 m0, s50, 0x2000
	v_lshl_add_u64 v[196:197], s[48:49], 0, v[202:203]
	global_load_lds_dwordx4 v[196:197], off
	s_mov_b32 m0, s56
	v_lshl_add_u64 v[196:197], s[46:47], 0, v[178:179]
	s_add_u32 s46, s46, 0x40000
	s_addc_u32 s47, s47, 0
	global_load_lds_dwordx4 v[196:197], off
	s_mov_b32 m0, s57
	v_lshl_add_u64 v[196:197], s[46:47], 0, v[178:179]
	global_load_lds_dwordx4 v[196:197], off
	s_waitcnt vmcnt(8)
	s_waitcnt lgkmcnt(0)
	s_barrier
	s_setprio 1
	s_waitcnt lgkmcnt(0)
	v_mfma_i32_16x16x64_i8 v[62:65], v[130:133], v[162:165], v[62:65]
	v_mfma_i32_16x16x64_i8 v[54:57], v[138:141], v[162:165], v[54:57]
	v_mfma_i32_16x16x64_i8 v[46:49], v[130:133], v[170:173], v[46:49]
	v_mfma_i32_16x16x64_i8 v[38:41], v[138:141], v[170:173], v[38:41]
	v_mfma_i32_16x16x64_i8 v[30:33], v[130:133], v[180:183], v[30:33]
	v_mfma_i32_16x16x64_i8 v[22:25], v[138:141], v[180:183], v[22:25]
	v_mfma_i32_16x16x64_i8 v[14:17], v[130:133], v[188:191], v[14:17]
	v_mfma_i32_16x16x64_i8 v[6:9], v[138:141], v[188:191], v[6:9]
	v_mfma_i32_16x16x64_i8 v[62:65], v[134:137], v[166:169], v[62:65]
	v_mfma_i32_16x16x64_i8 v[54:57], v[142:145], v[166:169], v[54:57]
	v_mfma_i32_16x16x64_i8 v[46:49], v[134:137], v[174:177], v[46:49]
	v_mfma_i32_16x16x64_i8 v[38:41], v[142:145], v[174:177], v[38:41]
	v_mfma_i32_16x16x64_i8 v[30:33], v[134:137], v[184:187], v[30:33]
	v_mfma_i32_16x16x64_i8 v[22:25], v[142:145], v[184:187], v[22:25]
	v_mfma_i32_16x16x64_i8 v[14:17], v[134:137], v[192:195], v[14:17]
	v_mfma_i32_16x16x64_i8 v[6:9], v[142:145], v[192:195], v[6:9]
	v_mfma_i32_16x16x64_i8 v[58:61], v[146:149], v[162:165], v[58:61]
	v_mfma_i32_16x16x64_i8 v[50:53], v[154:157], v[162:165], v[50:53]
	v_mfma_i32_16x16x64_i8 v[42:45], v[146:149], v[170:173], v[42:45]
	v_mfma_i32_16x16x64_i8 v[34:37], v[154:157], v[170:173], v[34:37]
	v_mfma_i32_16x16x64_i8 v[26:29], v[146:149], v[180:183], v[26:29]
	v_mfma_i32_16x16x64_i8 v[18:21], v[154:157], v[180:183], v[18:21]
	v_mfma_i32_16x16x64_i8 v[10:13], v[146:149], v[188:191], v[10:13]
	v_mfma_i32_16x16x64_i8 v[2:5], v[154:157], v[188:191], v[2:5]
	v_mfma_i32_16x16x64_i8 v[58:61], v[150:153], v[166:169], v[58:61]
	v_mfma_i32_16x16x64_i8 v[50:53], v[158:161], v[166:169], v[50:53]
	v_mfma_i32_16x16x64_i8 v[42:45], v[150:153], v[174:177], v[42:45]
	v_mfma_i32_16x16x64_i8 v[34:37], v[158:161], v[174:177], v[34:37]
	v_mfma_i32_16x16x64_i8 v[26:29], v[150:153], v[184:187], v[26:29]
	v_mfma_i32_16x16x64_i8 v[18:21], v[158:161], v[184:187], v[18:21]
	v_mfma_i32_16x16x64_i8 v[10:13], v[150:153], v[192:195], v[10:13]
	v_mfma_i32_16x16x64_i8 v[2:5], v[158:161], v[192:195], v[2:5]
	s_setprio 0
	s_barrier
	s_add_i32 s65, s65, 2
	s_add_u32 s23, s23, 0x100
	s_addc_u32 s62, s62, 0
	s_add_u32 s63, s63, 0x100
	s_addc_u32 s64, s64, 0
	s_cmp_gt_u32 s65, 13
	s_cbranch_scc0 .LBB0_1214
	s_and_b64 vcc, exec, s[18:19]
	s_cbranch_vccz .LBB0_1217
	s_barrier

.LBB0_1286:
	s_cmpk_eq_i32 s71, 0x54
	s_cselect_b32 s54, s48, s9
	s_cselect_b32 s55, s49, s27
	s_cselect_b32 s52, s50, s28
	s_cselect_b32 s53, s51, s29
	s_add_u32 s46, s54, 0x80
	s_addc_u32 s47, s55, 0
	s_add_i32 s74, 0, 0x10000
	s_add_i32 s75, 0, 0x14000
	v_add_u32_e32 v142, s74, v207
	v_add_u32_e32 v158, s75, v207
	s_waitcnt lgkmcnt(0)
	ds_read_b128 v[130:133], v142
	ds_read_b128 v[134:137], v142 offset:1024
	ds_read_b128 v[138:141], v142 offset:2048
	ds_read_b128 v[142:145], v142 offset:3072
	ds_read_b128 v[146:149], v158
	ds_read_b128 v[150:153], v158 offset:1024
	ds_read_b128 v[154:157], v158 offset:2048
	ds_read_b128 v[158:161], v158 offset:3072
	s_mov_b64 s[72:73], s[44:45]
	ds_read_b128 v[162:165], v237
	ds_read_b128 v[166:169], v237 offset:1024
	ds_read_b128 v[170:173], v237 offset:2048
	ds_read_b128 v[174:177], v237 offset:3072
	ds_read_b128 v[178:181], v237 offset:4096
	ds_read_b128 v[182:185], v237 offset:5120
	ds_read_b128 v[188:191], v237 offset:6144
	ds_read_b128 v[192:195], v237 offset:7168
	s_add_i32 m0, s58, 0xc000
	v_lshl_add_u64 v[196:197], s[72:73], 0, v[186:187]
	s_add_u32 s72, s72, 0xb0000
	s_addc_u32 s73, s73, 0
	global_load_lds_dwordx4 v[196:197], off
	s_add_i32 m0, s58, 0xe000
	v_lshl_add_u64 v[196:197], s[72:73], 0, v[186:187]
	global_load_lds_dwordx4 v[196:197], off
	s_waitcnt vmcnt(8)
	s_waitcnt lgkmcnt(0)
	s_barrier
	s_setprio 1
	s_waitcnt lgkmcnt(0)
	v_mfma_f32_16x16x32_bf16 v[2:5], v[130:133], v[162:165], v[2:5]
	v_mfma_f32_16x16x32_bf16 v[6:9], v[138:141], v[162:165], v[6:9]
	v_mfma_f32_16x16x32_bf16 v[14:17], v[130:133], v[170:173], v[14:17]
	v_mfma_f32_16x16x32_bf16 v[22:25], v[138:141], v[170:173], v[22:25]
	v_mfma_f32_16x16x32_bf16 v[30:33], v[130:133], v[178:181], v[30:33]
	v_mfma_f32_16x16x32_bf16 v[38:41], v[138:141], v[178:181], v[38:41]
	v_mfma_f32_16x16x32_bf16 v[46:49], v[130:133], v[188:191], v[46:49]
	v_mfma_f32_16x16x32_bf16 v[54:57], v[138:141], v[188:191], v[54:57]
	v_mfma_f32_16x16x32_bf16 v[2:5], v[134:137], v[166:169], v[2:5]
	v_mfma_f32_16x16x32_bf16 v[6:9], v[142:145], v[166:169], v[6:9]
	v_mfma_f32_16x16x32_bf16 v[14:17], v[134:137], v[174:177], v[14:17]
	v_mfma_f32_16x16x32_bf16 v[22:25], v[142:145], v[174:177], v[22:25]
	v_mfma_f32_16x16x32_bf16 v[30:33], v[134:137], v[182:185], v[30:33]
	v_mfma_f32_16x16x32_bf16 v[38:41], v[142:145], v[182:185], v[38:41]
	v_mfma_f32_16x16x32_bf16 v[46:49], v[134:137], v[192:195], v[46:49]
	v_mfma_f32_16x16x32_bf16 v[54:57], v[142:145], v[192:195], v[54:57]
	v_mfma_f32_16x16x32_bf16 v[10:13], v[146:149], v[162:165], v[10:13]
	v_mfma_f32_16x16x32_bf16 v[18:21], v[154:157], v[162:165], v[18:21]
	v_mfma_f32_16x16x32_bf16 v[26:29], v[146:149], v[170:173], v[26:29]
	v_mfma_f32_16x16x32_bf16 v[34:37], v[154:157], v[170:173], v[34:37]
	v_mfma_f32_16x16x32_bf16 v[42:45], v[146:149], v[178:181], v[42:45]
	v_mfma_f32_16x16x32_bf16 v[50:53], v[154:157], v[178:181], v[50:53]
	v_mfma_f32_16x16x32_bf16 v[58:61], v[146:149], v[188:191], v[58:61]
	v_mfma_f32_16x16x32_bf16 v[62:65], v[154:157], v[188:191], v[62:65]
	v_mfma_f32_16x16x32_bf16 v[10:13], v[150:153], v[166:169], v[10:13]
	v_mfma_f32_16x16x32_bf16 v[18:21], v[158:161], v[166:169], v[18:21]
	v_mfma_f32_16x16x32_bf16 v[26:29], v[150:153], v[174:177], v[26:29]
	v_mfma_f32_16x16x32_bf16 v[34:37], v[158:161], v[174:177], v[34:37]
	v_mfma_f32_16x16x32_bf16 v[42:45], v[150:153], v[182:185], v[42:45]
	v_mfma_f32_16x16x32_bf16 v[50:53], v[158:161], v[182:185], v[50:53]
	v_mfma_f32_16x16x32_bf16 v[58:61], v[150:153], v[192:195], v[58:61]
	v_mfma_f32_16x16x32_bf16 v[62:65], v[158:161], v[192:195], v[62:65]
	s_setprio 0
	s_barrier
	s_mov_b64 s[72:73], s[52:53]
	ds_read_b128 v[162:165], v237 offset:16384
	ds_read_b128 v[166:169], v237 offset:17408
	ds_read_b128 v[170:173], v237 offset:18432
	ds_read_b128 v[174:177], v237 offset:19456
	ds_read_b128 v[178:181], v237 offset:20480
	ds_read_b128 v[182:185], v237 offset:21504
	ds_read_b128 v[188:191], v237 offset:22528
	ds_read_b128 v[192:195], v237 offset:23552
	s_add_i32 s74, s74, s57
	v_lshl_add_u64 v[196:197], s[72:73], 0, v[202:203]
	s_add_u32 s72, s72, 0xb0000
	s_mov_b32 m0, s74
	s_addc_u32 s73, s73, 0
	global_load_lds_dwordx4 v[196:197], off
	s_add_i32 m0, s74, 0x2000
	v_lshl_add_u64 v[196:197], s[72:73], 0, v[202:203]
	s_add_u32 s72, s52, 0x160000
	s_addc_u32 s73, s53, 0
	global_load_lds_dwordx4 v[196:197], off
	s_add_i32 s74, s75, s57
	v_lshl_add_u64 v[196:197], s[72:73], 0, v[202:203]
	s_add_u32 s72, s72, 0xb0000
	s_mov_b32 m0, s74
	s_addc_u32 s73, s73, 0
	global_load_lds_dwordx4 v[196:197], off
	s_add_i32 m0, s74, 0x2000
	v_lshl_add_u64 v[196:197], s[72:73], 0, v[202:203]
	s_mov_b64 s[72:73], s[54:55]
	global_load_lds_dwordx4 v[196:197], off
	s_mov_b32 m0, s58
	v_lshl_add_u64 v[196:197], s[72:73], 0, v[186:187]
	s_add_u32 s72, s72, 0xb0000
	s_addc_u32 s73, s73, 0
	global_load_lds_dwordx4 v[196:197], off
	s_mov_b32 m0, s59
	v_lshl_add_u64 v[196:197], s[72:73], 0, v[186:187]
	global_load_lds_dwordx4 v[196:197], off
	s_waitcnt vmcnt(8)
	s_waitcnt lgkmcnt(0)
	s_barrier
	s_setprio 1
	s_waitcnt lgkmcnt(0)
	v_mfma_f32_16x16x32_bf16 v[66:69], v[130:133], v[162:165], v[66:69]
	v_mfma_f32_16x16x32_bf16 v[70:73], v[138:141], v[162:165], v[70:73]
	v_mfma_f32_16x16x32_bf16 v[74:77], v[130:133], v[170:173], v[74:77]
	v_mfma_f32_16x16x32_bf16 v[78:81], v[138:141], v[170:173], v[78:81]
	v_mfma_f32_16x16x32_bf16 v[86:89], v[130:133], v[178:181], v[86:89]
	v_mfma_f32_16x16x32_bf16 v[94:97], v[138:141], v[178:181], v[94:97]
	v_mfma_f32_16x16x32_bf16 v[102:105], v[130:133], v[188:191], v[102:105]
	v_mfma_f32_16x16x32_bf16 v[110:113], v[138:141], v[188:191], v[110:113]
	v_mfma_f32_16x16x32_bf16 v[66:69], v[134:137], v[166:169], v[66:69]
	v_mfma_f32_16x16x32_bf16 v[70:73], v[142:145], v[166:169], v[70:73]
	v_mfma_f32_16x16x32_bf16 v[74:77], v[134:137], v[174:177], v[74:77]
	v_mfma_f32_16x16x32_bf16 v[78:81], v[142:145], v[174:177], v[78:81]
	v_mfma_f32_16x16x32_bf16 v[86:89], v[134:137], v[182:185], v[86:89]
	v_mfma_f32_16x16x32_bf16 v[94:97], v[142:145], v[182:185], v[94:97]
	v_mfma_f32_16x16x32_bf16 v[102:105], v[134:137], v[192:195], v[102:105]
	v_mfma_f32_16x16x32_bf16 v[110:113], v[142:145], v[192:195], v[110:113]
	v_mfma_f32_16x16x32_bf16 v[82:85], v[146:149], v[162:165], v[82:85]
	v_mfma_f32_16x16x32_bf16 v[90:93], v[154:157], v[162:165], v[90:93]
	v_mfma_f32_16x16x32_bf16 v[98:101], v[146:149], v[170:173], v[98:101]
	v_mfma_f32_16x16x32_bf16 v[106:109], v[154:157], v[170:173], v[106:109]
	v_mfma_f32_16x16x32_bf16 v[114:117], v[146:149], v[178:181], v[114:117]
	v_mfma_f32_16x16x32_bf16 v[118:121], v[154:157], v[178:181], v[118:121]
	v_mfma_f32_16x16x32_bf16 v[122:125], v[146:149], v[188:191], v[122:125]
	v_mfma_f32_16x16x32_bf16 v[126:129], v[154:157], v[188:191], v[126:129]
	v_mfma_f32_16x16x32_bf16 v[82:85], v[150:153], v[166:169], v[82:85]
	v_mfma_f32_16x16x32_bf16 v[90:93], v[158:161], v[166:169], v[90:93]
	v_mfma_f32_16x16x32_bf16 v[98:101], v[150:153], v[174:177], v[98:101]
	v_mfma_f32_16x16x32_bf16 v[106:109], v[158:161], v[174:177], v[106:109]
	v_mfma_f32_16x16x32_bf16 v[114:117], v[150:153], v[182:185], v[114:117]
	v_mfma_f32_16x16x32_bf16 v[118:121], v[158:161], v[182:185], v[118:121]
	v_mfma_f32_16x16x32_bf16 v[122:125], v[150:153], v[192:195], v[122:125]
	v_mfma_f32_16x16x32_bf16 v[126:129], v[158:161], v[192:195], v[126:129]
	s_setprio 0
	s_barrier
	s_add_i32 s72, 0, 0x18000
	s_add_i32 s73, 0, 0x1c000
	v_add_u32_e32 v142, s72, v207
	v_add_u32_e32 v158, s73, v207
	ds_read_b128 v[130:133], v142
	ds_read_b128 v[134:137], v142 offset:1024
	ds_read_b128 v[138:141], v142 offset:2048
	ds_read_b128 v[142:145], v142 offset:3072
	ds_read_b128 v[146:149], v158
	ds_read_b128 v[150:153], v158 offset:1024
	ds_read_b128 v[154:157], v158 offset:2048
	ds_read_b128 v[158:161], v158 offset:3072
	s_add_u32 s54, s54, 0x160000
	s_addc_u32 s55, s55, 0
	ds_read_b128 v[162:165], v237 offset:32768
	ds_read_b128 v[166:169], v237 offset:33792
	ds_read_b128 v[170:173], v237 offset:34816
	ds_read_b128 v[174:177], v237 offset:35840
	ds_read_b128 v[178:181], v237 offset:36864
	ds_read_b128 v[182:185], v237 offset:37888
	ds_read_b128 v[188:191], v237 offset:38912
	ds_read_b128 v[192:195], v237 offset:39936
	s_mov_b32 m0, s60
	v_lshl_add_u64 v[196:197], s[54:55], 0, v[186:187]
	s_add_u32 s54, s54, 0xb0000
	s_addc_u32 s55, s55, 0
	global_load_lds_dwordx4 v[196:197], off
	s_mov_b32 m0, s61
	v_lshl_add_u64 v[196:197], s[54:55], 0, v[186:187]
	global_load_lds_dwordx4 v[196:197], off
	s_waitcnt vmcnt(8)
	s_waitcnt lgkmcnt(0)
	s_barrier
	s_setprio 1
	s_waitcnt lgkmcnt(0)
	v_mfma_f32_16x16x32_bf16 v[2:5], v[130:133], v[162:165], v[2:5]
	v_mfma_f32_16x16x32_bf16 v[6:9], v[138:141], v[162:165], v[6:9]
	v_mfma_f32_16x16x32_bf16 v[14:17], v[130:133], v[170:173], v[14:17]
	v_mfma_f32_16x16x32_bf16 v[22:25], v[138:141], v[170:173], v[22:25]
	v_mfma_f32_16x16x32_bf16 v[30:33], v[130:133], v[178:181], v[30:33]
	v_mfma_f32_16x16x32_bf16 v[38:41], v[138:141], v[178:181], v[38:41]
	v_mfma_f32_16x16x32_bf16 v[46:49], v[130:133], v[188:191], v[46:49]
	v_mfma_f32_16x16x32_bf16 v[54:57], v[138:141], v[188:191], v[54:57]
	v_mfma_f32_16x16x32_bf16 v[2:5], v[134:137], v[166:169], v[2:5]
	v_mfma_f32_16x16x32_bf16 v[6:9], v[142:145], v[166:169], v[6:9]
	v_mfma_f32_16x16x32_bf16 v[14:17], v[134:137], v[174:177], v[14:17]
	v_mfma_f32_16x16x32_bf16 v[22:25], v[142:145], v[174:177], v[22:25]
	v_mfma_f32_16x16x32_bf16 v[30:33], v[134:137], v[182:185], v[30:33]
	v_mfma_f32_16x16x32_bf16 v[38:41], v[142:145], v[182:185], v[38:41]
	v_mfma_f32_16x16x32_bf16 v[46:49], v[134:137], v[192:195], v[46:49]
	v_mfma_f32_16x16x32_bf16 v[54:57], v[142:145], v[192:195], v[54:57]
	v_mfma_f32_16x16x32_bf16 v[10:13], v[146:149], v[162:165], v[10:13]
	v_mfma_f32_16x16x32_bf16 v[18:21], v[154:157], v[162:165], v[18:21]
	v_mfma_f32_16x16x32_bf16 v[26:29], v[146:149], v[170:173], v[26:29]
	v_mfma_f32_16x16x32_bf16 v[34:37], v[154:157], v[170:173], v[34:37]
	v_mfma_f32_16x16x32_bf16 v[42:45], v[146:149], v[178:181], v[42:45]
	v_mfma_f32_16x16x32_bf16 v[50:53], v[154:157], v[178:181], v[50:53]
	v_mfma_f32_16x16x32_bf16 v[58:61], v[146:149], v[188:191], v[58:61]
	v_mfma_f32_16x16x32_bf16 v[62:65], v[154:157], v[188:191], v[62:65]
	v_mfma_f32_16x16x32_bf16 v[10:13], v[150:153], v[166:169], v[10:13]
	v_mfma_f32_16x16x32_bf16 v[18:21], v[158:161], v[166:169], v[18:21]
	v_mfma_f32_16x16x32_bf16 v[26:29], v[150:153], v[174:177], v[26:29]
	v_mfma_f32_16x16x32_bf16 v[34:37], v[158:161], v[174:177], v[34:37]
	v_mfma_f32_16x16x32_bf16 v[42:45], v[150:153], v[182:185], v[42:45]
	v_mfma_f32_16x16x32_bf16 v[50:53], v[158:161], v[182:185], v[50:53]
	v_mfma_f32_16x16x32_bf16 v[58:61], v[150:153], v[192:195], v[58:61]
	v_mfma_f32_16x16x32_bf16 v[62:65], v[158:161], v[192:195], v[62:65]
	s_setprio 0
	s_barrier
	s_add_u32 s54, s52, 0x80
	s_addc_u32 s55, s53, 0
	ds_read_b128 v[162:165], v237 offset:49152
	ds_read_b128 v[166:169], v237 offset:50176
	ds_read_b128 v[170:173], v237 offset:51200
	ds_read_b128 v[174:177], v237 offset:52224
	ds_read_b128 v[178:181], v237 offset:53248
	ds_read_b128 v[182:185], v237 offset:54272
	ds_read_b128 v[188:191], v237 offset:55296
	ds_read_b128 v[192:195], v237 offset:56320
	s_add_i32 s72, s72, s57
	v_lshl_add_u64 v[196:197], s[54:55], 0, v[202:203]
	s_mov_b32 m0, s72
	s_add_u32 s54, s54, 0xb0000
	global_load_lds_dwordx4 v[196:197], off
	s_addc_u32 s55, s55, 0
	s_add_i32 m0, s72, 0x2000
	s_add_u32 s52, s52, 0x160080
	s_addc_u32 s53, s53, 0
	v_lshl_add_u64 v[196:197], s[54:55], 0, v[202:203]
	global_load_lds_dwordx4 v[196:197], off
	s_add_i32 s54, s73, s57
	v_lshl_add_u64 v[196:197], s[52:53], 0, v[202:203]
	s_add_u32 s52, s52, 0xb0000
	s_mov_b32 m0, s54
	s_addc_u32 s53, s53, 0
	global_load_lds_dwordx4 v[196:197], off
	s_add_i32 m0, s54, 0x2000
	v_lshl_add_u64 v[196:197], s[52:53], 0, v[202:203]
	global_load_lds_dwordx4 v[196:197], off
	s_mov_b32 m0, s62
	v_lshl_add_u64 v[196:197], s[46:47], 0, v[186:187]
	s_add_u32 s46, s46, 0xb0000
	s_addc_u32 s47, s47, 0
	global_load_lds_dwordx4 v[196:197], off
	s_mov_b32 m0, s63
	v_lshl_add_u64 v[196:197], s[46:47], 0, v[186:187]
	global_load_lds_dwordx4 v[196:197], off
	s_waitcnt vmcnt(8)
	s_waitcnt lgkmcnt(0)
	s_barrier
	s_setprio 1
	s_waitcnt lgkmcnt(0)
	v_mfma_f32_16x16x32_bf16 v[66:69], v[130:133], v[162:165], v[66:69]
	v_mfma_f32_16x16x32_bf16 v[70:73], v[138:141], v[162:165], v[70:73]
	v_mfma_f32_16x16x32_bf16 v[74:77], v[130:133], v[170:173], v[74:77]
	v_mfma_f32_16x16x32_bf16 v[78:81], v[138:141], v[170:173], v[78:81]
	v_mfma_f32_16x16x32_bf16 v[86:89], v[130:133], v[178:181], v[86:89]
	v_mfma_f32_16x16x32_bf16 v[94:97], v[138:141], v[178:181], v[94:97]
	v_mfma_f32_16x16x32_bf16 v[102:105], v[130:133], v[188:191], v[102:105]
	v_mfma_f32_16x16x32_bf16 v[110:113], v[138:141], v[188:191], v[110:113]
	v_mfma_f32_16x16x32_bf16 v[66:69], v[134:137], v[166:169], v[66:69]
	v_mfma_f32_16x16x32_bf16 v[70:73], v[142:145], v[166:169], v[70:73]
	v_mfma_f32_16x16x32_bf16 v[74:77], v[134:137], v[174:177], v[74:77]
	v_mfma_f32_16x16x32_bf16 v[78:81], v[142:145], v[174:177], v[78:81]
	v_mfma_f32_16x16x32_bf16 v[86:89], v[134:137], v[182:185], v[86:89]
	v_mfma_f32_16x16x32_bf16 v[94:97], v[142:145], v[182:185], v[94:97]
	v_mfma_f32_16x16x32_bf16 v[102:105], v[134:137], v[192:195], v[102:105]
	v_mfma_f32_16x16x32_bf16 v[110:113], v[142:145], v[192:195], v[110:113]
	v_mfma_f32_16x16x32_bf16 v[82:85], v[146:149], v[162:165], v[82:85]
	v_mfma_f32_16x16x32_bf16 v[90:93], v[154:157], v[162:165], v[90:93]
	v_mfma_f32_16x16x32_bf16 v[98:101], v[146:149], v[170:173], v[98:101]
	v_mfma_f32_16x16x32_bf16 v[106:109], v[154:157], v[170:173], v[106:109]
	v_mfma_f32_16x16x32_bf16 v[114:117], v[146:149], v[178:181], v[114:117]
	v_mfma_f32_16x16x32_bf16 v[118:121], v[154:157], v[178:181], v[118:121]
	v_mfma_f32_16x16x32_bf16 v[122:125], v[146:149], v[188:191], v[122:125]
	v_mfma_f32_16x16x32_bf16 v[126:129], v[154:157], v[188:191], v[126:129]
	v_mfma_f32_16x16x32_bf16 v[82:85], v[150:153], v[166:169], v[82:85]
	v_mfma_f32_16x16x32_bf16 v[90:93], v[158:161], v[166:169], v[90:93]
	v_mfma_f32_16x16x32_bf16 v[98:101], v[150:153], v[174:177], v[98:101]
	v_mfma_f32_16x16x32_bf16 v[106:109], v[158:161], v[174:177], v[106:109]
	v_mfma_f32_16x16x32_bf16 v[114:117], v[150:153], v[182:185], v[114:117]
	v_mfma_f32_16x16x32_bf16 v[118:121], v[158:161], v[182:185], v[118:121]
	v_mfma_f32_16x16x32_bf16 v[122:125], v[150:153], v[192:195], v[122:125]
	v_mfma_f32_16x16x32_bf16 v[126:129], v[158:161], v[192:195], v[126:129]
	s_setprio 0
	s_barrier
	s_add_i32 s71, s71, 2
	s_add_u32 s9, s9, 0x100
	s_addc_u32 s27, s27, 0
	s_add_u32 s28, s28, 0x100
	s_addc_u32 s29, s29, 0
	s_add_u32 s44, s44, 0x100
	s_addc_u32 s45, s45, 0
	s_cmpk_gt_u32 s71, 0x55
	s_cbranch_scc0 .LBB0_1286
	s_and_b64 vcc, exec, s[18:19]
	s_cbranch_vccz .LBB0_1289
	s_barrier
